# queue fillers (transposes + combine), code padded so the attention loop and the GEMM phases sit at the same addresses (mod 4 KiB) as before the restructuring
# baseline (speedup 1.0000x reference)
; DI unsigned cvt_pk_bf16(float lo, float hi) { unsigned r; asm("v_cvt_pk_bf16_f32 %0, %1, %2" : "=v"(r) : "v"(lo), "v"(hi)); return r; }
; DI void transpose_w(const float* __restrict__ W, int K, int N, bf16_t* __restrict__ Wt, int gtid, int gthreads) {
;   const int total = (K / 8) * N;
;   for (int id = gtid; id < total; id += gthreads) {
;     const int kc = id / N, n = id - kc * N;
;     const int rho = n & 255;
;     const int act = (n & ~255) + ((rho >> 5) & 3) * 64 + (rho >> 7) * 32 + ((rho >> 2) & 3) * 8 + ((rho >> 4) & 1) * 4 + (rho & 3);
;     const float* src = W + (size_t)(kc * 8) * N + act;
;     float v[8];
; #pragma unroll
;     for (int j = 0; j < 8; ++j) v[j] = src[(size_t)j * N];
;     uint4 o; o.x = cvt_pk_bf16(v[0], v[1]); o.y = cvt_pk_bf16(v[2], v[3]); o.z = cvt_pk_bf16(v[4], v[5]); o.w = cvt_pk_bf16(v[6], v[7]);
;     *(uint4*)(Wt + (size_t)n * K + kc * 8) = o;
;   }
; DI void phase_prep(const Params& p) {
;     ...
;   transpose_w(p.w_out, 1024, 1024, (bf16_t*)(p.ws + WS_WOUT), gtid, gthreads);
;   transpose_w(p.w_mlp_in, 1024, 4096, (bf16_t*)(p.ws + WS_WM1), gtid, gthreads);
;   transpose_w(p.w_mlp_out, 4096, 1024, (bf16_t*)(p.ws + WS_WM2), gtid, gthreads);
.LBB0_28:
	s_or_b64 exec, exec, s[6:7]
	s_branch .LBB0_39
	s_nop 0
	s_nop 0
	s_nop 0
	s_nop 0
	s_nop 0
	s_nop 0
	s_nop 0
	s_nop 0
	s_nop 0
	s_nop 0
	s_nop 0
	s_nop 0
	s_nop 0
	s_nop 0
	s_nop 0
	s_nop 0
	s_nop 0
	s_nop 0
	s_nop 0
	s_nop 0
	s_nop 0
	s_nop 0
	s_nop 0
	s_nop 0
	s_nop 0
	s_nop 0
	s_nop 0
	s_nop 0
	s_nop 0
	s_nop 0
	s_nop 0
	s_nop 0
	s_nop 0
	s_nop 0
	s_nop 0
	s_nop 0
	s_nop 0
	s_nop 0
	s_nop 0
	s_nop 0
	s_nop 0
	s_nop 0
	s_nop 0
	s_nop 0
	s_nop 0
	s_nop 0
	s_nop 0
	s_nop 0
	s_nop 0
	s_nop 0
	s_nop 0
	s_nop 0
	s_nop 0
	s_nop 0
	s_nop 0
	s_nop 0
	s_nop 0
	s_nop 0
	s_nop 0
	s_nop 0
	s_nop 0
	s_nop 0
	s_nop 0
	s_nop 0
	s_nop 0
	s_nop 0
	s_nop 0
	s_nop 0
	s_nop 0
	s_nop 0
	s_nop 0
	s_nop 0
	s_nop 0
	s_nop 0
	s_nop 0
	s_nop 0
	s_nop 0
	s_nop 0
	s_nop 0
	s_nop 0
	s_nop 0
	s_nop 0
	s_nop 0
	s_nop 0
	s_nop 0
	s_nop 0
	s_nop 0
	s_nop 0
	s_nop 0
	s_nop 0
	s_nop 0
	s_nop 0
	s_nop 0
	s_nop 0
	s_nop 0
	s_nop 0
	s_nop 0
	s_nop 0
	s_nop 0
	s_nop 0
	s_nop 0
	s_nop 0
	s_nop 0
	s_nop 0
	s_nop 0
	s_nop 0
	s_nop 0
	s_nop 0
	s_nop 0
	s_nop 0
	s_nop 0
	s_nop 0
	s_nop 0
	s_nop 0
	s_nop 0
	s_nop 0
	s_nop 0
	s_nop 0
	s_nop 0
	s_nop 0
	s_nop 0
	s_nop 0
	s_nop 0
	s_nop 0
	s_nop 0
	s_nop 0
	s_nop 0
	s_nop 0
	s_nop 0
	s_nop 0
	s_nop 0
	s_nop 0
	s_nop 0
	s_nop 0
	s_nop 0
	s_nop 0
	s_nop 0
	s_nop 0
	s_nop 0
	s_nop 0
	s_nop 0
	s_nop 0
	s_nop 0
	s_nop 0
	s_nop 0
	s_nop 0
	s_nop 0
	s_nop 0
	s_nop 0
	s_nop 0
	s_nop 0
	s_nop 0
	s_nop 0
	s_nop 0
	s_nop 0
	s_nop 0
	s_nop 0
	s_nop 0
	s_nop 0
	s_nop 0
	s_nop 0
	s_nop 0
	s_nop 0
	s_nop 0
	s_nop 0
	s_nop 0
	s_nop 0
	s_nop 0
	s_nop 0
	s_nop 0
	s_nop 0
	s_nop 0
	s_nop 0
	s_nop 0
	s_nop 0
	s_nop 0
	s_nop 0
	s_nop 0
	s_nop 0
	s_nop 0
	s_nop 0
	s_nop 0
	s_nop 0
	s_nop 0
	s_nop 0
	s_nop 0
	s_nop 0
	s_nop 0
	s_nop 0
	s_nop 0
	s_nop 0
	s_nop 0
	s_nop 0
	s_nop 0
	s_nop 0
	s_nop 0
	s_nop 0
	s_nop 0
	s_nop 0
	s_nop 0
	s_nop 0
	s_nop 0
	s_nop 0
	s_nop 0
	s_nop 0
	s_nop 0
	s_nop 0
	s_nop 0
	s_nop 0
	s_nop 0
	s_nop 0
	s_nop 0
	s_nop 0
	s_nop 0
	s_nop 0
	s_nop 0
	s_nop 0
	s_nop 0
	s_nop 0
	s_nop 0
	s_nop 0
	s_nop 0
	s_nop 0
	s_nop 0
	s_nop 0
	s_nop 0
	s_nop 0
	s_nop 0
	s_nop 0
	s_nop 0
	s_nop 0
	s_nop 0
	s_nop 0
	s_nop 0
	s_nop 0
	s_nop 0
	s_nop 0
	s_nop 0
	s_nop 0
	s_nop 0
	s_nop 0
	s_nop 0
	s_nop 0
	s_nop 0
	s_nop 0
	s_nop 0
	s_nop 0
	s_nop 0
	s_nop 0
	s_nop 0
	s_nop 0
	s_nop 0
	s_nop 0
	s_nop 0
	s_nop 0
	s_nop 0
	s_nop 0
	s_nop 0
	s_nop 0
	s_nop 0
	s_nop 0
	s_nop 0
	s_nop 0
	s_nop 0
	s_nop 0
	s_nop 0
	s_nop 0
	s_nop 0
	s_nop 0
	s_nop 0
	s_nop 0
	s_nop 0
	s_nop 0
	s_nop 0
	s_nop 0
	s_nop 0
	s_nop 0
	s_nop 0
	s_nop 0
	s_nop 0
	s_nop 0
	s_nop 0
	s_nop 0
	s_nop 0
	s_nop 0
	s_nop 0
	s_nop 0
	s_nop 0
	s_nop 0
	s_nop 0
	s_nop 0
	s_nop 0
	s_nop 0
	s_nop 0
	s_nop 0
	s_nop 0
	s_nop 0
	s_nop 0
	s_nop 0
	s_nop 0
	s_nop 0
	s_nop 0
	s_nop 0
	s_nop 0
	s_nop 0
	s_nop 0
	s_nop 0
	s_nop 0
	s_nop 0
	s_nop 0
	s_nop 0
	s_nop 0
	s_nop 0
	s_nop 0
	s_nop 0
	s_nop 0
	s_nop 0
	s_nop 0
	s_nop 0
	s_nop 0
	s_nop 0
	s_nop 0
	s_nop 0
	s_nop 0
	s_nop 0
	s_nop 0
	s_nop 0
	s_nop 0
	s_nop 0
	s_nop 0
	s_nop 0
	s_nop 0
	s_nop 0
	s_nop 0
	s_nop 0
	s_nop 0
	s_nop 0
	s_nop 0
	s_nop 0
	s_nop 0
	s_nop 0
	s_nop 0
	s_nop 0
	s_nop 0
	s_nop 0
	s_nop 0
	s_nop 0
	s_nop 0
	s_nop 0
	s_nop 0
	s_nop 0
	s_nop 0
	s_nop 0
	s_nop 0
	s_nop 0
	s_nop 0
	s_nop 0
	s_nop 0
	s_nop 0
	s_nop 0
	s_nop 0
	s_nop 0
	s_nop 0
	s_nop 0
	s_nop 0
	s_nop 0
	s_nop 0
	s_nop 0
	s_nop 0
	s_nop 0
	s_nop 0
	s_nop 0

; DI void phase_mixer(const Params& p) {
;     ...
;   for (;;) {
;     __syncthreads();
;     if (threadIdx.x == 0) *sItem = (int)atomicAdd(ctr, 1u);
;     __syncthreads();
;     const int it = *sItem;
;     if (it >= 48 + 2048) break;
;     if (it < 48) hgrn_item(p, it); else attn_item(p, it - 48);
.LBB0_958:
	s_or_b64 exec, exec, s[0:1]
	s_waitcnt lgkmcnt(0)
	s_barrier
	ds_read_b32 v0, v213
	s_waitcnt lgkmcnt(0)
	v_readfirstlane_b32 s12, v0
	s_mov_b64 s[0:1], -1
	s_cmpk_gt_i32 s12, 0x82f
	s_nop 0
	s_cbranch_scc1 .Lq2_dispatch
	s_cmp_gt_i32 s12, 47
	s_cbranch_scc0 .LBB0_1000
	s_sub_i32 s5, s12, 48
	s_lshl_b32 s3, s5, 5
	s_cmpk_gt_u32 s5, 0x3ff
	s_cbranch_scc0 .LBB0_962
	s_and_b32 s0, s3, 0xe000
	s_lshr_b32 s4, s5, 6
	s_and_b32 s10, s5, 63
	s_add_i32 s6, s0, 0xffff8000
	s_mov_b64 s[0:1], 0

.LBB0_1007:
	s_andn2_b64 vcc, exec, s[84:85]
	s_cbranch_vccnz .LBB0_1002
	s_add_i32 s45, s41, -1
	s_and_b64 s[84:85], s[4:5], exec
	s_cselect_b32 s40, s80, s45
	s_lshl_b32 s84, s40, 6
	s_add_i32 vcc_lo, s84, s78
	s_ashr_i32 vcc_hi, vcc_lo, 31
	s_lshl_b64 s[42:43], vcc, 10
	v_lshl_add_u64 v[32:33], v[56:57], 0, s[42:43]
	global_load_dword v74, v[32:33], off
	v_lshl_add_u64 v[32:33], v[62:63], 0, s[42:43]
	s_add_i32 s42, vcc_lo, s48
	s_ashr_i32 s43, s42, 31
	s_lshl_b64 vcc, s[42:43], 10
	s_add_i32 s42, s42, s48
	global_load_dword v75, v[32:33], off
	v_lshl_add_u64 v[32:33], v[56:57], 0, vcc
	s_ashr_i32 s43, s42, 31
	global_load_dword v76, v[32:33], off
	v_lshl_add_u64 v[32:33], v[62:63], 0, vcc
	s_lshl_b64 vcc, s[42:43], 10
	s_add_i32 s42, s42, s48
	global_load_dword v77, v[32:33], off
	v_lshl_add_u64 v[32:33], v[56:57], 0, vcc
	s_ashr_i32 s43, s42, 31
	global_load_dword v78, v[32:33], off
	v_lshl_add_u64 v[32:33], v[62:63], 0, vcc
	s_lshl_b64 vcc, s[42:43], 10
	s_add_i32 s42, s42, s48
	global_load_dword v79, v[32:33], off
	v_lshl_add_u64 v[32:33], v[56:57], 0, vcc
	s_ashr_i32 s43, s42, 31
	global_load_dword v80, v[32:33], off
	v_lshl_add_u64 v[32:33], v[62:63], 0, vcc
	s_lshl_b64 vcc, s[42:43], 10
	s_add_i32 s42, s42, s48
	global_load_dword v87, v[32:33], off
	v_lshl_add_u64 v[32:33], v[56:57], 0, vcc
	s_ashr_i32 s43, s42, 31
	global_load_dword v88, v[32:33], off
	v_lshl_add_u64 v[32:33], v[62:63], 0, vcc
	s_lshl_b64 vcc, s[42:43], 10
	s_add_i32 s42, s42, s48
	global_load_dword v89, v[32:33], off
	v_lshl_add_u64 v[32:33], v[56:57], 0, vcc
	s_ashr_i32 s43, s42, 31
	global_load_dword v90, v[32:33], off
	v_lshl_add_u64 v[32:33], v[62:63], 0, vcc
	s_lshl_b64 vcc, s[42:43], 10
	s_add_i32 s42, s42, s48
	global_load_dword v91, v[32:33], off
	v_lshl_add_u64 v[32:33], v[56:57], 0, vcc
	s_ashr_i32 s43, s42, 31
	global_load_dword v92, v[32:33], off
	v_lshl_add_u64 v[32:33], v[62:63], 0, vcc
	s_lshl_b64 s[42:43], s[42:43], 10
	global_load_dword v93, v[32:33], off
	v_lshl_add_u64 v[32:33], v[56:57], 0, s[42:43]
	s_ashr_i32 s85, s84, 31
	s_add_i32 s40, s96, 0x4000
	global_load_dword v94, v[32:33], off
	v_lshl_add_u64 v[32:33], v[62:63], 0, s[42:43]
	s_lshl_b64 s[42:43], s[84:85], 1
	s_and_b32 s84, s40, 0x4000
	s_add_i32 s84, s1, s84
	global_load_dword v103, v[32:33], off
	v_lshl_add_u64 v[32:33], v[58:59], 0, s[42:43]
	s_mov_b32 m0, s84
	s_nop 0
	global_load_lds_dwordx4 v[32:33], off
	v_lshl_add_u64 v[32:33], v[60:61], 0, s[42:43]
	s_add_i32 m0, s84, 0x400
	s_nop 0
	global_load_lds_dwordx4 v[32:33], off
	s_branch .LBB0_1002
.Lhg_done:
	s_waitcnt vmcnt(0)
	s_barrier
	v_readlane_b32 s84, v236, 5
	v_readlane_b32 s85, v236, 6
	s_nop 3
	s_and_saveexec_b64 s[0:1], s[84:85]
	s_cbranch_execz .Lhg_sig_done
	buffer_wbl2 sc1
	s_waitcnt vmcnt(0)
	v_mov_b32_e32 v0, 0
	v_mov_b32_e32 v1, 1
	global_atomic_add v0, v1, s[82:83] offset:64
.Lhg_sig_done:
	s_or_b64 exec, exec, s[0:1]
	s_branch .LBB0_952

; DI unsigned cvt_pk_bf16(float lo, float hi) { unsigned r; asm("v_cvt_pk_bf16_f32 %0, %1, %2" : "=v"(r) : "v"(lo), "v"(hi)); return r; }
; DI void phase_combine(const Params& p) {
;     ...
;   for (int tok = blockIdx.x * 8 + wave; tok < NTOK; tok += gridDim.x * 8) {
;     unsigned a[4], b[4], g[4];
; #pragma unroll
;     for (int hh = 0; hh < 4; ++hh) { const size_t idx = ((size_t)tok * 512 + hh * 128 + lane * 2) >> 1; a[hh] = ofw[idx]; b[hh] = obw[idx]; g[hh] = GH[idx]; }
; #pragma unroll
;     for (int hh = 0; hh < 4; ++hh) {
;       const float o0 = __uint_as_float(a[hh] << 16) + __uint_as_float(b[hh] << 16), o1 = __uint_as_float(a[hh] & 0xffff0000u) + __uint_as_float(b[hh] & 0xffff0000u);
;       const float ss = wave_sum(o0 * o0 + o1 * o1);
;       const float rstd = rsqrtf(ss * (1.f / 128.f) + EPSN);
;       const float g0 = __uint_as_float(g[hh] << 16), g1 = __uint_as_float(g[hh] & 0xffff0000u);
;       *(unsigned*)(OC + (size_t)tok * 1024 + 512 + hh * 128 + lane * 2) = cvt_pk_bf16(o0 * rstd * w0 * g0, o1 * rstd * w1 * g1);
;     }
.Lcq_loop:
	s_waitcnt vmcnt(36)
	v_lshlrev_b32_e32 v64, 16, v104
	v_lshlrev_b32_e32 v76, 16, v108
	v_and_b32_e32 v68, 0xffff0000, v104
	v_and_b32_e32 v80, 0xffff0000, v108
	v_add_f32_e32 v64, v64, v76
	v_add_f32_e32 v68, v68, v80
	v_mul_f32_e32 v72, v64, v64
	v_mul_f32_e32 v76, v68, v68
	v_add_f32_e32 v72, v72, v76
	v_lshlrev_b32_e32 v65, 16, v105
	v_lshlrev_b32_e32 v77, 16, v109
	v_and_b32_e32 v69, 0xffff0000, v105
	v_and_b32_e32 v81, 0xffff0000, v109
	v_add_f32_e32 v65, v65, v77
	v_add_f32_e32 v69, v69, v81
	v_mul_f32_e32 v73, v65, v65
	v_mul_f32_e32 v77, v69, v69
	v_add_f32_e32 v73, v73, v77
	v_lshlrev_b32_e32 v66, 16, v106
	v_lshlrev_b32_e32 v78, 16, v110
	v_and_b32_e32 v70, 0xffff0000, v106
	v_and_b32_e32 v82, 0xffff0000, v110
	v_add_f32_e32 v66, v66, v78
	v_add_f32_e32 v70, v70, v82
	v_mul_f32_e32 v74, v66, v66
	v_mul_f32_e32 v78, v70, v70
	v_add_f32_e32 v74, v74, v78
	v_lshlrev_b32_e32 v67, 16, v107
	v_lshlrev_b32_e32 v79, 16, v111
	v_and_b32_e32 v71, 0xffff0000, v107
	v_and_b32_e32 v83, 0xffff0000, v111
	v_add_f32_e32 v67, v67, v79
	v_add_f32_e32 v71, v71, v83
	v_mul_f32_e32 v75, v67, v67
	v_mul_f32_e32 v79, v71, v71
	v_add_f32_e32 v75, v75, v79
	ds_bpermute_b32 v76, v8, v72
	ds_bpermute_b32 v77, v8, v73
	ds_bpermute_b32 v78, v8, v74
	ds_bpermute_b32 v79, v8, v75
	s_waitcnt lgkmcnt(3)
	v_add_f32_e32 v72, v72, v76
	s_waitcnt lgkmcnt(2)
	v_add_f32_e32 v73, v73, v77
	s_waitcnt lgkmcnt(1)
	v_add_f32_e32 v74, v74, v78
	s_waitcnt lgkmcnt(0)
	v_add_f32_e32 v75, v75, v79
	ds_bpermute_b32 v76, v9, v72
	ds_bpermute_b32 v77, v9, v73
	ds_bpermute_b32 v78, v9, v74
	ds_bpermute_b32 v79, v9, v75
	s_waitcnt lgkmcnt(3)
	v_add_f32_e32 v72, v72, v76
	s_waitcnt lgkmcnt(2)
	v_add_f32_e32 v73, v73, v77
	s_waitcnt lgkmcnt(1)
	v_add_f32_e32 v74, v74, v78
	s_waitcnt lgkmcnt(0)
	v_add_f32_e32 v75, v75, v79
	ds_bpermute_b32 v76, v10, v72
	ds_bpermute_b32 v77, v10, v73
	ds_bpermute_b32 v78, v10, v74
	ds_bpermute_b32 v79, v10, v75
	s_waitcnt lgkmcnt(3)
	v_add_f32_e32 v72, v72, v76
	s_waitcnt lgkmcnt(2)
	v_add_f32_e32 v73, v73, v77
	s_waitcnt lgkmcnt(1)
	v_add_f32_e32 v74, v74, v78
	s_waitcnt lgkmcnt(0)
	v_add_f32_e32 v75, v75, v79
	ds_bpermute_b32 v76, v11, v72
	ds_bpermute_b32 v77, v11, v73
	ds_bpermute_b32 v78, v11, v74
	ds_bpermute_b32 v79, v11, v75
	s_waitcnt lgkmcnt(3)
	v_add_f32_e32 v72, v72, v76
	s_waitcnt lgkmcnt(2)
	v_add_f32_e32 v73, v73, v77
	s_waitcnt lgkmcnt(1)
	v_add_f32_e32 v74, v74, v78
	s_waitcnt lgkmcnt(0)
	v_add_f32_e32 v75, v75, v79
	ds_bpermute_b32 v76, v12, v72
	ds_bpermute_b32 v77, v12, v73
	ds_bpermute_b32 v78, v12, v74
	ds_bpermute_b32 v79, v12, v75
	s_waitcnt lgkmcnt(3)
	v_add_f32_e32 v72, v72, v76
	s_waitcnt lgkmcnt(2)
	v_add_f32_e32 v73, v73, v77
	s_waitcnt lgkmcnt(1)
	v_add_f32_e32 v74, v74, v78
	s_waitcnt lgkmcnt(0)
	v_add_f32_e32 v75, v75, v79
	ds_bpermute_b32 v76, v13, v72
	ds_bpermute_b32 v77, v13, v73
	ds_bpermute_b32 v78, v13, v74
	ds_bpermute_b32 v79, v13, v75
	s_waitcnt lgkmcnt(3)
	v_add_f32_e32 v72, v72, v76
	s_waitcnt lgkmcnt(2)
	v_add_f32_e32 v73, v73, v77
	s_waitcnt lgkmcnt(1)
	v_add_f32_e32 v74, v74, v78
	s_waitcnt lgkmcnt(0)
	v_add_f32_e32 v75, v75, v79
	v_fmamk_f32 v80, v72, 0x3c000000, v14
	v_mul_f32_e32 v76, 0x4b800000, v80
	v_cmp_gt_f32_e32 vcc, s14, v80
	s_nop 1
	v_cndmask_b32_e32 v80, v80, v76, vcc
	v_rsq_f32_e32 v80, v80
	s_nop 0
	v_mul_f32_e32 v76, 0x45800000, v80
	v_cndmask_b32_e32 v80, v80, v76, vcc
	v_mul_f32_e32 v64, v64, v80
	v_mul_f32_e32 v68, v68, v80
	v_mul_f32_e32 v64, v2, v64
	v_mul_f32_e32 v68, v3, v68
	v_lshlrev_b32_e32 v76, 16, v112
	v_and_b32_e32 v72, 0xffff0000, v112
	v_mul_f32_e32 v64, v64, v76
	v_mul_f32_e32 v68, v68, v72
	v_cvt_pk_bf16_f32 v64, v64, v68
	global_store_dword v[98:99], v64, off
	v_fmamk_f32 v81, v73, 0x3c000000, v14
	v_mul_f32_e32 v77, 0x4b800000, v81
	v_cmp_gt_f32_e32 vcc, s14, v81
	s_nop 1
	v_cndmask_b32_e32 v81, v81, v77, vcc
	v_rsq_f32_e32 v81, v81
	s_nop 0
	v_mul_f32_e32 v77, 0x45800000, v81
	v_cndmask_b32_e32 v81, v81, v77, vcc
	v_mul_f32_e32 v65, v65, v81
	v_mul_f32_e32 v69, v69, v81
	v_mul_f32_e32 v65, v2, v65
	v_mul_f32_e32 v69, v3, v69
	v_lshlrev_b32_e32 v77, 16, v113
	v_and_b32_e32 v73, 0xffff0000, v113
	v_mul_f32_e32 v65, v65, v77
	v_mul_f32_e32 v69, v69, v73
	v_cvt_pk_bf16_f32 v65, v65, v69
	global_store_dword v[98:99], v65, off offset:256
	v_fmamk_f32 v82, v74, 0x3c000000, v14
	v_mul_f32_e32 v78, 0x4b800000, v82
	v_cmp_gt_f32_e32 vcc, s14, v82
	s_nop 1
	v_cndmask_b32_e32 v82, v82, v78, vcc
	v_rsq_f32_e32 v82, v82
	s_nop 0
	v_mul_f32_e32 v78, 0x45800000, v82
	v_cndmask_b32_e32 v82, v82, v78, vcc
	v_mul_f32_e32 v66, v66, v82
	v_mul_f32_e32 v70, v70, v82
	v_mul_f32_e32 v66, v2, v66
	v_mul_f32_e32 v70, v3, v70
	v_lshlrev_b32_e32 v78, 16, v114
	v_and_b32_e32 v74, 0xffff0000, v114
	v_mul_f32_e32 v66, v66, v78
	v_mul_f32_e32 v70, v70, v74
	v_cvt_pk_bf16_f32 v66, v66, v70
	global_store_dword v[98:99], v66, off offset:512
	v_fmamk_f32 v83, v75, 0x3c000000, v14
	v_mul_f32_e32 v79, 0x4b800000, v83
	v_cmp_gt_f32_e32 vcc, s14, v83
	s_nop 1
	v_cndmask_b32_e32 v83, v83, v79, vcc
	v_rsq_f32_e32 v83, v83
	s_nop 0
	v_mul_f32_e32 v79, 0x45800000, v83
	v_cndmask_b32_e32 v83, v83, v79, vcc
	v_mul_f32_e32 v67, v67, v83
	v_mul_f32_e32 v71, v71, v83
	v_mul_f32_e32 v67, v2, v67
	v_mul_f32_e32 v71, v3, v71
	v_lshlrev_b32_e32 v79, 16, v115
	v_and_b32_e32 v75, 0xffff0000, v115
	v_mul_f32_e32 v67, v67, v79
	v_mul_f32_e32 v71, v71, v75
	v_cvt_pk_bf16_f32 v67, v67, v71
	global_store_dword v[98:99], v67, off offset:768
	v_lshl_add_u64 v[98:99], v[98:99], 0, s[16:17]
	global_load_dword v104, v[92:93], off
	global_load_dword v105, v[92:93], off offset:256
	global_load_dword v106, v[92:93], off offset:512
	global_load_dword v107, v[92:93], off offset:768
	global_load_dword v108, v[94:95], off
	global_load_dword v109, v[94:95], off offset:256
	global_load_dword v110, v[94:95], off offset:512
	global_load_dword v111, v[94:95], off offset:768
	global_load_dword v112, v[96:97], off
	global_load_dword v113, v[96:97], off offset:256
	global_load_dword v114, v[96:97], off offset:512
	global_load_dword v115, v[96:97], off offset:768
	v_lshl_add_u64 v[92:93], v[92:93], 0, s[10:11]
	v_lshl_add_u64 v[94:95], v[94:95], 0, s[10:11]
	v_lshl_add_u64 v[96:97], v[96:97], 0, s[10:11]
	s_waitcnt vmcnt(40)
; DI unsigned cvt_pk_bf16(float lo, float hi) { unsigned r; asm("v_cvt_pk_bf16_f32 %0, %1, %2" : "=v"(r) : "v"(lo), "v"(hi)); return r; }
; DI void phase_combine(const Params& p) {
;     ...
; #pragma unroll
;     for (int hh = 0; hh < 4; ++hh) {
;       const float o0 = __uint_as_float(a[hh] << 16) + __uint_as_float(b[hh] << 16), o1 = __uint_as_float(a[hh] & 0xffff0000u) + __uint_as_float(b[hh] & 0xffff0000u);
;       const float ss = wave_sum(o0 * o0 + o1 * o1);
;       const float rstd = rsqrtf(ss * (1.f / 128.f) + EPSN);
;       const float g0 = __uint_as_float(g[hh] << 16), g1 = __uint_as_float(g[hh] & 0xffff0000u);
;       *(unsigned*)(OC + (size_t)tok * 1024 + 512 + hh * 128 + lane * 2) = cvt_pk_bf16(o0 * rstd * w0 * g0, o1 * rstd * w1 * g1);
;     }
	v_lshlrev_b32_e32 v64, 16, v116
	v_lshlrev_b32_e32 v76, 16, v120
	v_and_b32_e32 v68, 0xffff0000, v116
	v_and_b32_e32 v80, 0xffff0000, v120
	v_add_f32_e32 v64, v64, v76
	v_add_f32_e32 v68, v68, v80
	v_mul_f32_e32 v72, v64, v64
	v_mul_f32_e32 v76, v68, v68
	v_add_f32_e32 v72, v72, v76
	v_lshlrev_b32_e32 v65, 16, v117
	v_lshlrev_b32_e32 v77, 16, v121
	v_and_b32_e32 v69, 0xffff0000, v117
	v_and_b32_e32 v81, 0xffff0000, v121
	v_add_f32_e32 v65, v65, v77
	v_add_f32_e32 v69, v69, v81
	v_mul_f32_e32 v73, v65, v65
	v_mul_f32_e32 v77, v69, v69
	v_add_f32_e32 v73, v73, v77
	v_lshlrev_b32_e32 v66, 16, v118
	v_lshlrev_b32_e32 v78, 16, v122
	v_and_b32_e32 v70, 0xffff0000, v118
	v_and_b32_e32 v82, 0xffff0000, v122
	v_add_f32_e32 v66, v66, v78
	v_add_f32_e32 v70, v70, v82
	v_mul_f32_e32 v74, v66, v66
	v_mul_f32_e32 v78, v70, v70
	v_add_f32_e32 v74, v74, v78
	v_lshlrev_b32_e32 v67, 16, v119
	v_lshlrev_b32_e32 v79, 16, v123
	v_and_b32_e32 v71, 0xffff0000, v119
	v_and_b32_e32 v83, 0xffff0000, v123
	v_add_f32_e32 v67, v67, v79
	v_add_f32_e32 v71, v71, v83
	v_mul_f32_e32 v75, v67, v67
	v_mul_f32_e32 v79, v71, v71
	v_add_f32_e32 v75, v75, v79
	ds_bpermute_b32 v76, v8, v72
	ds_bpermute_b32 v77, v8, v73
	ds_bpermute_b32 v78, v8, v74
	ds_bpermute_b32 v79, v8, v75
	s_waitcnt lgkmcnt(3)
	v_add_f32_e32 v72, v72, v76
	s_waitcnt lgkmcnt(2)
	v_add_f32_e32 v73, v73, v77
	s_waitcnt lgkmcnt(1)
	v_add_f32_e32 v74, v74, v78
	s_waitcnt lgkmcnt(0)
	v_add_f32_e32 v75, v75, v79
	ds_bpermute_b32 v76, v9, v72
	ds_bpermute_b32 v77, v9, v73
	ds_bpermute_b32 v78, v9, v74
	ds_bpermute_b32 v79, v9, v75
	s_waitcnt lgkmcnt(3)
	v_add_f32_e32 v72, v72, v76
	s_waitcnt lgkmcnt(2)
	v_add_f32_e32 v73, v73, v77
	s_waitcnt lgkmcnt(1)
	v_add_f32_e32 v74, v74, v78
	s_waitcnt lgkmcnt(0)
	v_add_f32_e32 v75, v75, v79
	ds_bpermute_b32 v76, v10, v72
	ds_bpermute_b32 v77, v10, v73
	ds_bpermute_b32 v78, v10, v74
	ds_bpermute_b32 v79, v10, v75
	s_waitcnt lgkmcnt(3)
	v_add_f32_e32 v72, v72, v76
	s_waitcnt lgkmcnt(2)
	v_add_f32_e32 v73, v73, v77
	s_waitcnt lgkmcnt(1)
	v_add_f32_e32 v74, v74, v78
	s_waitcnt lgkmcnt(0)
	v_add_f32_e32 v75, v75, v79
	ds_bpermute_b32 v76, v11, v72
	ds_bpermute_b32 v77, v11, v73
	ds_bpermute_b32 v78, v11, v74
	ds_bpermute_b32 v79, v11, v75
	s_waitcnt lgkmcnt(3)
	v_add_f32_e32 v72, v72, v76
	s_waitcnt lgkmcnt(2)
	v_add_f32_e32 v73, v73, v77
	s_waitcnt lgkmcnt(1)
	v_add_f32_e32 v74, v74, v78
	s_waitcnt lgkmcnt(0)
	v_add_f32_e32 v75, v75, v79
	ds_bpermute_b32 v76, v12, v72
	ds_bpermute_b32 v77, v12, v73
	ds_bpermute_b32 v78, v12, v74
	ds_bpermute_b32 v79, v12, v75
	s_waitcnt lgkmcnt(3)
	v_add_f32_e32 v72, v72, v76
	s_waitcnt lgkmcnt(2)
	v_add_f32_e32 v73, v73, v77
	s_waitcnt lgkmcnt(1)
	v_add_f32_e32 v74, v74, v78
	s_waitcnt lgkmcnt(0)
	v_add_f32_e32 v75, v75, v79
	ds_bpermute_b32 v76, v13, v72
	ds_bpermute_b32 v77, v13, v73
	ds_bpermute_b32 v78, v13, v74
	ds_bpermute_b32 v79, v13, v75
	s_waitcnt lgkmcnt(3)
	v_add_f32_e32 v72, v72, v76
	s_waitcnt lgkmcnt(2)
	v_add_f32_e32 v73, v73, v77
	s_waitcnt lgkmcnt(1)
	v_add_f32_e32 v74, v74, v78
	s_waitcnt lgkmcnt(0)
	v_add_f32_e32 v75, v75, v79
	v_fmamk_f32 v80, v72, 0x3c000000, v14
	v_mul_f32_e32 v76, 0x4b800000, v80
	v_cmp_gt_f32_e32 vcc, s14, v80
	s_nop 1
	v_cndmask_b32_e32 v80, v80, v76, vcc
	v_rsq_f32_e32 v80, v80
	s_nop 0
	v_mul_f32_e32 v76, 0x45800000, v80
	v_cndmask_b32_e32 v80, v80, v76, vcc
	v_mul_f32_e32 v64, v64, v80
	v_mul_f32_e32 v68, v68, v80
	v_mul_f32_e32 v64, v2, v64
	v_mul_f32_e32 v68, v3, v68
	v_lshlrev_b32_e32 v76, 16, v124
	v_and_b32_e32 v72, 0xffff0000, v124
	v_mul_f32_e32 v64, v64, v76
	v_mul_f32_e32 v68, v68, v72
	v_cvt_pk_bf16_f32 v64, v64, v68
	global_store_dword v[98:99], v64, off
	v_fmamk_f32 v81, v73, 0x3c000000, v14
	v_mul_f32_e32 v77, 0x4b800000, v81
	v_cmp_gt_f32_e32 vcc, s14, v81
	s_nop 1
	v_cndmask_b32_e32 v81, v81, v77, vcc
	v_rsq_f32_e32 v81, v81
	s_nop 0
	v_mul_f32_e32 v77, 0x45800000, v81
	v_cndmask_b32_e32 v81, v81, v77, vcc
	v_mul_f32_e32 v65, v65, v81
	v_mul_f32_e32 v69, v69, v81
	v_mul_f32_e32 v65, v2, v65
	v_mul_f32_e32 v69, v3, v69
	v_lshlrev_b32_e32 v77, 16, v125
	v_and_b32_e32 v73, 0xffff0000, v125
	v_mul_f32_e32 v65, v65, v77
	v_mul_f32_e32 v69, v69, v73
	v_cvt_pk_bf16_f32 v65, v65, v69
	global_store_dword v[98:99], v65, off offset:256
	v_fmamk_f32 v82, v74, 0x3c000000, v14
	v_mul_f32_e32 v78, 0x4b800000, v82
	v_cmp_gt_f32_e32 vcc, s14, v82
	s_nop 1
	v_cndmask_b32_e32 v82, v82, v78, vcc
	v_rsq_f32_e32 v82, v82
	s_nop 0
	v_mul_f32_e32 v78, 0x45800000, v82
	v_cndmask_b32_e32 v82, v82, v78, vcc
	v_mul_f32_e32 v66, v66, v82
	v_mul_f32_e32 v70, v70, v82
	v_mul_f32_e32 v66, v2, v66
	v_mul_f32_e32 v70, v3, v70
	v_lshlrev_b32_e32 v78, 16, v126
	v_and_b32_e32 v74, 0xffff0000, v126
	v_mul_f32_e32 v66, v66, v78
	v_mul_f32_e32 v70, v70, v74
	v_cvt_pk_bf16_f32 v66, v66, v70
	global_store_dword v[98:99], v66, off offset:512
	v_fmamk_f32 v83, v75, 0x3c000000, v14
	v_mul_f32_e32 v79, 0x4b800000, v83
	v_cmp_gt_f32_e32 vcc, s14, v83
	s_nop 1
	v_cndmask_b32_e32 v83, v83, v79, vcc
	v_rsq_f32_e32 v83, v83
	s_nop 0
	v_mul_f32_e32 v79, 0x45800000, v83
	v_cndmask_b32_e32 v83, v83, v79, vcc
	v_mul_f32_e32 v67, v67, v83
	v_mul_f32_e32 v71, v71, v83
	v_mul_f32_e32 v67, v2, v67
	v_mul_f32_e32 v71, v3, v71
	v_lshlrev_b32_e32 v79, 16, v127
	v_and_b32_e32 v75, 0xffff0000, v127
	v_mul_f32_e32 v67, v67, v79
	v_mul_f32_e32 v71, v71, v75
	v_cvt_pk_bf16_f32 v67, v67, v71
	global_store_dword v[98:99], v67, off offset:768
	v_lshl_add_u64 v[98:99], v[98:99], 0, s[16:17]
	global_load_dword v116, v[92:93], off
	global_load_dword v117, v[92:93], off offset:256
	global_load_dword v118, v[92:93], off offset:512
	global_load_dword v119, v[92:93], off offset:768
	global_load_dword v120, v[94:95], off
	global_load_dword v121, v[94:95], off offset:256
	global_load_dword v122, v[94:95], off offset:512
	global_load_dword v123, v[94:95], off offset:768
	global_load_dword v124, v[96:97], off
	global_load_dword v125, v[96:97], off offset:256
	global_load_dword v126, v[96:97], off offset:512
	global_load_dword v127, v[96:97], off offset:768
	v_lshl_add_u64 v[92:93], v[92:93], 0, s[10:11]
	v_lshl_add_u64 v[94:95], v[94:95], 0, s[10:11]
	v_lshl_add_u64 v[96:97], v[96:97], 0, s[10:11]
	s_waitcnt vmcnt(44)
; DI unsigned cvt_pk_bf16(float lo, float hi) { unsigned r; asm("v_cvt_pk_bf16_f32 %0, %1, %2" : "=v"(r) : "v"(lo), "v"(hi)); return r; }
; DI void phase_combine(const Params& p) {
;     ...
; #pragma unroll
;     for (int hh = 0; hh < 4; ++hh) {
;       const float o0 = __uint_as_float(a[hh] << 16) + __uint_as_float(b[hh] << 16), o1 = __uint_as_float(a[hh] & 0xffff0000u) + __uint_as_float(b[hh] & 0xffff0000u);
;       const float ss = wave_sum(o0 * o0 + o1 * o1);
;       const float rstd = rsqrtf(ss * (1.f / 128.f) + EPSN);
;       const float g0 = __uint_as_float(g[hh] << 16), g1 = __uint_as_float(g[hh] & 0xffff0000u);
;       *(unsigned*)(OC + (size_t)tok * 1024 + 512 + hh * 128 + lane * 2) = cvt_pk_bf16(o0 * rstd * w0 * g0, o1 * rstd * w1 * g1);
;     }
	v_lshlrev_b32_e32 v64, 16, v128
	v_lshlrev_b32_e32 v76, 16, v132
	v_and_b32_e32 v68, 0xffff0000, v128
	v_and_b32_e32 v80, 0xffff0000, v132
	v_add_f32_e32 v64, v64, v76
	v_add_f32_e32 v68, v68, v80
	v_mul_f32_e32 v72, v64, v64
	v_mul_f32_e32 v76, v68, v68
	v_add_f32_e32 v72, v72, v76
	v_lshlrev_b32_e32 v65, 16, v129
	v_lshlrev_b32_e32 v77, 16, v133
	v_and_b32_e32 v69, 0xffff0000, v129
	v_and_b32_e32 v81, 0xffff0000, v133
	v_add_f32_e32 v65, v65, v77
	v_add_f32_e32 v69, v69, v81
	v_mul_f32_e32 v73, v65, v65
	v_mul_f32_e32 v77, v69, v69
	v_add_f32_e32 v73, v73, v77
	v_lshlrev_b32_e32 v66, 16, v130
	v_lshlrev_b32_e32 v78, 16, v134
	v_and_b32_e32 v70, 0xffff0000, v130
	v_and_b32_e32 v82, 0xffff0000, v134
	v_add_f32_e32 v66, v66, v78
	v_add_f32_e32 v70, v70, v82
	v_mul_f32_e32 v74, v66, v66
	v_mul_f32_e32 v78, v70, v70
	v_add_f32_e32 v74, v74, v78
	v_lshlrev_b32_e32 v67, 16, v131
	v_lshlrev_b32_e32 v79, 16, v135
	v_and_b32_e32 v71, 0xffff0000, v131
	v_and_b32_e32 v83, 0xffff0000, v135
	v_add_f32_e32 v67, v67, v79
	v_add_f32_e32 v71, v71, v83
	v_mul_f32_e32 v75, v67, v67
	v_mul_f32_e32 v79, v71, v71
	v_add_f32_e32 v75, v75, v79
	ds_bpermute_b32 v76, v8, v72
	ds_bpermute_b32 v77, v8, v73
	ds_bpermute_b32 v78, v8, v74
	ds_bpermute_b32 v79, v8, v75
	s_waitcnt lgkmcnt(3)
	v_add_f32_e32 v72, v72, v76
	s_waitcnt lgkmcnt(2)
	v_add_f32_e32 v73, v73, v77
	s_waitcnt lgkmcnt(1)
	v_add_f32_e32 v74, v74, v78
	s_waitcnt lgkmcnt(0)
	v_add_f32_e32 v75, v75, v79
	ds_bpermute_b32 v76, v9, v72
	ds_bpermute_b32 v77, v9, v73
	ds_bpermute_b32 v78, v9, v74
	ds_bpermute_b32 v79, v9, v75
	s_waitcnt lgkmcnt(3)
	v_add_f32_e32 v72, v72, v76
	s_waitcnt lgkmcnt(2)
	v_add_f32_e32 v73, v73, v77
	s_waitcnt lgkmcnt(1)
	v_add_f32_e32 v74, v74, v78
	s_waitcnt lgkmcnt(0)
	v_add_f32_e32 v75, v75, v79
	ds_bpermute_b32 v76, v10, v72
	ds_bpermute_b32 v77, v10, v73
	ds_bpermute_b32 v78, v10, v74
	ds_bpermute_b32 v79, v10, v75
	s_waitcnt lgkmcnt(3)
	v_add_f32_e32 v72, v72, v76
	s_waitcnt lgkmcnt(2)
	v_add_f32_e32 v73, v73, v77
	s_waitcnt lgkmcnt(1)
	v_add_f32_e32 v74, v74, v78
	s_waitcnt lgkmcnt(0)
	v_add_f32_e32 v75, v75, v79
	ds_bpermute_b32 v76, v11, v72
	ds_bpermute_b32 v77, v11, v73
	ds_bpermute_b32 v78, v11, v74
	ds_bpermute_b32 v79, v11, v75
	s_waitcnt lgkmcnt(3)
	v_add_f32_e32 v72, v72, v76
	s_waitcnt lgkmcnt(2)
	v_add_f32_e32 v73, v73, v77
	s_waitcnt lgkmcnt(1)
	v_add_f32_e32 v74, v74, v78
	s_waitcnt lgkmcnt(0)
	v_add_f32_e32 v75, v75, v79
	ds_bpermute_b32 v76, v12, v72
	ds_bpermute_b32 v77, v12, v73
	ds_bpermute_b32 v78, v12, v74
	ds_bpermute_b32 v79, v12, v75
	s_waitcnt lgkmcnt(3)
	v_add_f32_e32 v72, v72, v76
	s_waitcnt lgkmcnt(2)
	v_add_f32_e32 v73, v73, v77
	s_waitcnt lgkmcnt(1)
	v_add_f32_e32 v74, v74, v78
	s_waitcnt lgkmcnt(0)
	v_add_f32_e32 v75, v75, v79
	ds_bpermute_b32 v76, v13, v72
	ds_bpermute_b32 v77, v13, v73
	ds_bpermute_b32 v78, v13, v74
	ds_bpermute_b32 v79, v13, v75
	s_waitcnt lgkmcnt(3)
	v_add_f32_e32 v72, v72, v76
	s_waitcnt lgkmcnt(2)
	v_add_f32_e32 v73, v73, v77
	s_waitcnt lgkmcnt(1)
	v_add_f32_e32 v74, v74, v78
	s_waitcnt lgkmcnt(0)
	v_add_f32_e32 v75, v75, v79
	v_fmamk_f32 v80, v72, 0x3c000000, v14
	v_mul_f32_e32 v76, 0x4b800000, v80
	v_cmp_gt_f32_e32 vcc, s14, v80
	s_nop 1
	v_cndmask_b32_e32 v80, v80, v76, vcc
	v_rsq_f32_e32 v80, v80
	s_nop 0
	v_mul_f32_e32 v76, 0x45800000, v80
	v_cndmask_b32_e32 v80, v80, v76, vcc
	v_mul_f32_e32 v64, v64, v80
	v_mul_f32_e32 v68, v68, v80
	v_mul_f32_e32 v64, v2, v64
	v_mul_f32_e32 v68, v3, v68
	v_lshlrev_b32_e32 v76, 16, v136
	v_and_b32_e32 v72, 0xffff0000, v136
	v_mul_f32_e32 v64, v64, v76
	v_mul_f32_e32 v68, v68, v72
	v_cvt_pk_bf16_f32 v64, v64, v68
	global_store_dword v[98:99], v64, off
	v_fmamk_f32 v81, v73, 0x3c000000, v14
	v_mul_f32_e32 v77, 0x4b800000, v81
	v_cmp_gt_f32_e32 vcc, s14, v81
	s_nop 1
	v_cndmask_b32_e32 v81, v81, v77, vcc
	v_rsq_f32_e32 v81, v81
	s_nop 0
	v_mul_f32_e32 v77, 0x45800000, v81
	v_cndmask_b32_e32 v81, v81, v77, vcc
	v_mul_f32_e32 v65, v65, v81
	v_mul_f32_e32 v69, v69, v81
	v_mul_f32_e32 v65, v2, v65
	v_mul_f32_e32 v69, v3, v69
	v_lshlrev_b32_e32 v77, 16, v137
	v_and_b32_e32 v73, 0xffff0000, v137
	v_mul_f32_e32 v65, v65, v77
	v_mul_f32_e32 v69, v69, v73
	v_cvt_pk_bf16_f32 v65, v65, v69
	global_store_dword v[98:99], v65, off offset:256
	v_fmamk_f32 v82, v74, 0x3c000000, v14
	v_mul_f32_e32 v78, 0x4b800000, v82
	v_cmp_gt_f32_e32 vcc, s14, v82
	s_nop 1
	v_cndmask_b32_e32 v82, v82, v78, vcc
	v_rsq_f32_e32 v82, v82
	s_nop 0
	v_mul_f32_e32 v78, 0x45800000, v82
	v_cndmask_b32_e32 v82, v82, v78, vcc
	v_mul_f32_e32 v66, v66, v82
	v_mul_f32_e32 v70, v70, v82
	v_mul_f32_e32 v66, v2, v66
	v_mul_f32_e32 v70, v3, v70
	v_lshlrev_b32_e32 v78, 16, v138
	v_and_b32_e32 v74, 0xffff0000, v138
	v_mul_f32_e32 v66, v66, v78
	v_mul_f32_e32 v70, v70, v74
	v_cvt_pk_bf16_f32 v66, v66, v70
	global_store_dword v[98:99], v66, off offset:512
	v_fmamk_f32 v83, v75, 0x3c000000, v14
	v_mul_f32_e32 v79, 0x4b800000, v83
	v_cmp_gt_f32_e32 vcc, s14, v83
	s_nop 1
	v_cndmask_b32_e32 v83, v83, v79, vcc
	v_rsq_f32_e32 v83, v83
	s_nop 0
	v_mul_f32_e32 v79, 0x45800000, v83
	v_cndmask_b32_e32 v83, v83, v79, vcc
	v_mul_f32_e32 v67, v67, v83
	v_mul_f32_e32 v71, v71, v83
	v_mul_f32_e32 v67, v2, v67
	v_mul_f32_e32 v71, v3, v71
	v_lshlrev_b32_e32 v79, 16, v139
	v_and_b32_e32 v75, 0xffff0000, v139
	v_mul_f32_e32 v67, v67, v79
	v_mul_f32_e32 v71, v71, v75
	v_cvt_pk_bf16_f32 v67, v67, v71
	global_store_dword v[98:99], v67, off offset:768
	v_lshl_add_u64 v[98:99], v[98:99], 0, s[16:17]
	global_load_dword v128, v[92:93], off
	global_load_dword v129, v[92:93], off offset:256
	global_load_dword v130, v[92:93], off offset:512
	global_load_dword v131, v[92:93], off offset:768
	global_load_dword v132, v[94:95], off
	global_load_dword v133, v[94:95], off offset:256
	global_load_dword v134, v[94:95], off offset:512
	global_load_dword v135, v[94:95], off offset:768
	global_load_dword v136, v[96:97], off
	global_load_dword v137, v[96:97], off offset:256
	global_load_dword v138, v[96:97], off offset:512
	global_load_dword v139, v[96:97], off offset:768
	v_lshl_add_u64 v[92:93], v[92:93], 0, s[10:11]
	v_lshl_add_u64 v[94:95], v[94:95], 0, s[10:11]
	v_lshl_add_u64 v[96:97], v[96:97], 0, s[10:11]
	s_waitcnt vmcnt(48)
; DI unsigned cvt_pk_bf16(float lo, float hi) { unsigned r; asm("v_cvt_pk_bf16_f32 %0, %1, %2" : "=v"(r) : "v"(lo), "v"(hi)); return r; }
; DI void phase_combine(const Params& p) {
;     ...
; #pragma unroll
;     for (int hh = 0; hh < 4; ++hh) {
;       const float o0 = __uint_as_float(a[hh] << 16) + __uint_as_float(b[hh] << 16), o1 = __uint_as_float(a[hh] & 0xffff0000u) + __uint_as_float(b[hh] & 0xffff0000u);
;       const float ss = wave_sum(o0 * o0 + o1 * o1);
;       const float rstd = rsqrtf(ss * (1.f / 128.f) + EPSN);
;       const float g0 = __uint_as_float(g[hh] << 16), g1 = __uint_as_float(g[hh] & 0xffff0000u);
;       *(unsigned*)(OC + (size_t)tok * 1024 + 512 + hh * 128 + lane * 2) = cvt_pk_bf16(o0 * rstd * w0 * g0, o1 * rstd * w1 * g1);
;     }
	v_lshlrev_b32_e32 v64, 16, v140
	v_lshlrev_b32_e32 v76, 16, v144
	v_and_b32_e32 v68, 0xffff0000, v140
	v_and_b32_e32 v80, 0xffff0000, v144
	v_add_f32_e32 v64, v64, v76
	v_add_f32_e32 v68, v68, v80
	v_mul_f32_e32 v72, v64, v64
	v_mul_f32_e32 v76, v68, v68
	v_add_f32_e32 v72, v72, v76
	v_lshlrev_b32_e32 v65, 16, v141
	v_lshlrev_b32_e32 v77, 16, v145
	v_and_b32_e32 v69, 0xffff0000, v141
	v_and_b32_e32 v81, 0xffff0000, v145
	v_add_f32_e32 v65, v65, v77
	v_add_f32_e32 v69, v69, v81
	v_mul_f32_e32 v73, v65, v65
	v_mul_f32_e32 v77, v69, v69
	v_add_f32_e32 v73, v73, v77
	v_lshlrev_b32_e32 v66, 16, v142
	v_lshlrev_b32_e32 v78, 16, v146
	v_and_b32_e32 v70, 0xffff0000, v142
	v_and_b32_e32 v82, 0xffff0000, v146
	v_add_f32_e32 v66, v66, v78
	v_add_f32_e32 v70, v70, v82
	v_mul_f32_e32 v74, v66, v66
	v_mul_f32_e32 v78, v70, v70
	v_add_f32_e32 v74, v74, v78
	v_lshlrev_b32_e32 v67, 16, v143
	v_lshlrev_b32_e32 v79, 16, v147
	v_and_b32_e32 v71, 0xffff0000, v143
	v_and_b32_e32 v83, 0xffff0000, v147
	v_add_f32_e32 v67, v67, v79
	v_add_f32_e32 v71, v71, v83
	v_mul_f32_e32 v75, v67, v67
	v_mul_f32_e32 v79, v71, v71
	v_add_f32_e32 v75, v75, v79
	ds_bpermute_b32 v76, v8, v72
	ds_bpermute_b32 v77, v8, v73
	ds_bpermute_b32 v78, v8, v74
	ds_bpermute_b32 v79, v8, v75
	s_waitcnt lgkmcnt(3)
	v_add_f32_e32 v72, v72, v76
	s_waitcnt lgkmcnt(2)
	v_add_f32_e32 v73, v73, v77
	s_waitcnt lgkmcnt(1)
	v_add_f32_e32 v74, v74, v78
	s_waitcnt lgkmcnt(0)
	v_add_f32_e32 v75, v75, v79
	ds_bpermute_b32 v76, v9, v72
	ds_bpermute_b32 v77, v9, v73
	ds_bpermute_b32 v78, v9, v74
	ds_bpermute_b32 v79, v9, v75
	s_waitcnt lgkmcnt(3)
	v_add_f32_e32 v72, v72, v76
	s_waitcnt lgkmcnt(2)
	v_add_f32_e32 v73, v73, v77
	s_waitcnt lgkmcnt(1)
	v_add_f32_e32 v74, v74, v78
	s_waitcnt lgkmcnt(0)
	v_add_f32_e32 v75, v75, v79
	ds_bpermute_b32 v76, v10, v72
	ds_bpermute_b32 v77, v10, v73
	ds_bpermute_b32 v78, v10, v74
	ds_bpermute_b32 v79, v10, v75
	s_waitcnt lgkmcnt(3)
	v_add_f32_e32 v72, v72, v76
	s_waitcnt lgkmcnt(2)
	v_add_f32_e32 v73, v73, v77
	s_waitcnt lgkmcnt(1)
	v_add_f32_e32 v74, v74, v78
	s_waitcnt lgkmcnt(0)
	v_add_f32_e32 v75, v75, v79
	ds_bpermute_b32 v76, v11, v72
	ds_bpermute_b32 v77, v11, v73
	ds_bpermute_b32 v78, v11, v74
	ds_bpermute_b32 v79, v11, v75
	s_waitcnt lgkmcnt(3)
	v_add_f32_e32 v72, v72, v76
	s_waitcnt lgkmcnt(2)
	v_add_f32_e32 v73, v73, v77
	s_waitcnt lgkmcnt(1)
	v_add_f32_e32 v74, v74, v78
	s_waitcnt lgkmcnt(0)
	v_add_f32_e32 v75, v75, v79
	ds_bpermute_b32 v76, v12, v72
	ds_bpermute_b32 v77, v12, v73
	ds_bpermute_b32 v78, v12, v74
	ds_bpermute_b32 v79, v12, v75
	s_waitcnt lgkmcnt(3)
	v_add_f32_e32 v72, v72, v76
	s_waitcnt lgkmcnt(2)
	v_add_f32_e32 v73, v73, v77
	s_waitcnt lgkmcnt(1)
	v_add_f32_e32 v74, v74, v78
	s_waitcnt lgkmcnt(0)
	v_add_f32_e32 v75, v75, v79
	ds_bpermute_b32 v76, v13, v72
	ds_bpermute_b32 v77, v13, v73
	ds_bpermute_b32 v78, v13, v74
	ds_bpermute_b32 v79, v13, v75
	s_waitcnt lgkmcnt(3)
	v_add_f32_e32 v72, v72, v76
	s_waitcnt lgkmcnt(2)
	v_add_f32_e32 v73, v73, v77
	s_waitcnt lgkmcnt(1)
	v_add_f32_e32 v74, v74, v78
	s_waitcnt lgkmcnt(0)
	v_add_f32_e32 v75, v75, v79
	v_fmamk_f32 v80, v72, 0x3c000000, v14
	v_mul_f32_e32 v76, 0x4b800000, v80
	v_cmp_gt_f32_e32 vcc, s14, v80
	s_nop 1
	v_cndmask_b32_e32 v80, v80, v76, vcc
	v_rsq_f32_e32 v80, v80
	s_nop 0
	v_mul_f32_e32 v76, 0x45800000, v80
	v_cndmask_b32_e32 v80, v80, v76, vcc
	v_mul_f32_e32 v64, v64, v80
	v_mul_f32_e32 v68, v68, v80
	v_mul_f32_e32 v64, v2, v64
	v_mul_f32_e32 v68, v3, v68
	v_lshlrev_b32_e32 v76, 16, v148
	v_and_b32_e32 v72, 0xffff0000, v148
	v_mul_f32_e32 v64, v64, v76
	v_mul_f32_e32 v68, v68, v72
	v_cvt_pk_bf16_f32 v64, v64, v68
	global_store_dword v[98:99], v64, off
	v_fmamk_f32 v81, v73, 0x3c000000, v14
	v_mul_f32_e32 v77, 0x4b800000, v81
	v_cmp_gt_f32_e32 vcc, s14, v81
	s_nop 1
	v_cndmask_b32_e32 v81, v81, v77, vcc
	v_rsq_f32_e32 v81, v81
	s_nop 0
	v_mul_f32_e32 v77, 0x45800000, v81
	v_cndmask_b32_e32 v81, v81, v77, vcc
	v_mul_f32_e32 v65, v65, v81
	v_mul_f32_e32 v69, v69, v81
	v_mul_f32_e32 v65, v2, v65
	v_mul_f32_e32 v69, v3, v69
	v_lshlrev_b32_e32 v77, 16, v149
	v_and_b32_e32 v73, 0xffff0000, v149
	v_mul_f32_e32 v65, v65, v77
	v_mul_f32_e32 v69, v69, v73
	v_cvt_pk_bf16_f32 v65, v65, v69
	global_store_dword v[98:99], v65, off offset:256
	v_fmamk_f32 v82, v74, 0x3c000000, v14
	v_mul_f32_e32 v78, 0x4b800000, v82
	v_cmp_gt_f32_e32 vcc, s14, v82
	s_nop 1
	v_cndmask_b32_e32 v82, v82, v78, vcc
	v_rsq_f32_e32 v82, v82
	s_nop 0
	v_mul_f32_e32 v78, 0x45800000, v82
	v_cndmask_b32_e32 v82, v82, v78, vcc
	v_mul_f32_e32 v66, v66, v82
	v_mul_f32_e32 v70, v70, v82
	v_mul_f32_e32 v66, v2, v66
	v_mul_f32_e32 v70, v3, v70
	v_lshlrev_b32_e32 v78, 16, v150
	v_and_b32_e32 v74, 0xffff0000, v150
	v_mul_f32_e32 v66, v66, v78
	v_mul_f32_e32 v70, v70, v74
	v_cvt_pk_bf16_f32 v66, v66, v70
	global_store_dword v[98:99], v66, off offset:512
	v_fmamk_f32 v83, v75, 0x3c000000, v14
	v_mul_f32_e32 v79, 0x4b800000, v83
	v_cmp_gt_f32_e32 vcc, s14, v83
	s_nop 1
	v_cndmask_b32_e32 v83, v83, v79, vcc
	v_rsq_f32_e32 v83, v83
	s_nop 0
	v_mul_f32_e32 v79, 0x45800000, v83
	v_cndmask_b32_e32 v83, v83, v79, vcc
	v_mul_f32_e32 v67, v67, v83
	v_mul_f32_e32 v71, v71, v83
	v_mul_f32_e32 v67, v2, v67
	v_mul_f32_e32 v71, v3, v71
	v_lshlrev_b32_e32 v79, 16, v151
	v_and_b32_e32 v75, 0xffff0000, v151
	v_mul_f32_e32 v67, v67, v79
	v_mul_f32_e32 v71, v71, v75
	v_cvt_pk_bf16_f32 v67, v67, v71
	global_store_dword v[98:99], v67, off offset:768
	v_lshl_add_u64 v[98:99], v[98:99], 0, s[16:17]
	global_load_dword v140, v[92:93], off
	global_load_dword v141, v[92:93], off offset:256
	global_load_dword v142, v[92:93], off offset:512
	global_load_dword v143, v[92:93], off offset:768
	global_load_dword v144, v[94:95], off
	global_load_dword v145, v[94:95], off offset:256
	global_load_dword v146, v[94:95], off offset:512
	global_load_dword v147, v[94:95], off offset:768
	global_load_dword v148, v[96:97], off
	global_load_dword v149, v[96:97], off offset:256
	global_load_dword v150, v[96:97], off offset:512
	global_load_dword v151, v[96:97], off offset:768
	v_lshl_add_u64 v[92:93], v[92:93], 0, s[10:11]
	v_lshl_add_u64 v[94:95], v[94:95], 0, s[10:11]
	v_lshl_add_u64 v[96:97], v[96:97], 0, s[10:11]
	s_sub_i32 s98, s98, 1
	s_cmp_lg_u32 s98, 0
	s_cbranch_scc1 .Lcq_loop
; DI unsigned cvt_pk_bf16(float lo, float hi) { unsigned r; asm("v_cvt_pk_bf16_f32 %0, %1, %2" : "=v"(r) : "v"(lo), "v"(hi)); return r; }
; DI void phase_combine(const Params& p) {
;     ...
; #pragma unroll
;     for (int hh = 0; hh < 4; ++hh) {
;       const float o0 = __uint_as_float(a[hh] << 16) + __uint_as_float(b[hh] << 16), o1 = __uint_as_float(a[hh] & 0xffff0000u) + __uint_as_float(b[hh] & 0xffff0000u);
;       const float ss = wave_sum(o0 * o0 + o1 * o1);
;       const float rstd = rsqrtf(ss * (1.f / 128.f) + EPSN);
;       const float g0 = __uint_as_float(g[hh] << 16), g1 = __uint_as_float(g[hh] & 0xffff0000u);
;       *(unsigned*)(OC + (size_t)tok * 1024 + 512 + hh * 128 + lane * 2) = cvt_pk_bf16(o0 * rstd * w0 * g0, o1 * rstd * w1 * g1);
;     }
	s_waitcnt vmcnt(48)
	v_lshlrev_b32_e32 v64, 16, v104
	v_lshlrev_b32_e32 v76, 16, v108
	v_and_b32_e32 v68, 0xffff0000, v104
	v_and_b32_e32 v80, 0xffff0000, v108
	v_add_f32_e32 v64, v64, v76
	v_add_f32_e32 v68, v68, v80
	v_mul_f32_e32 v72, v64, v64
	v_mul_f32_e32 v76, v68, v68
	v_add_f32_e32 v72, v72, v76
	v_lshlrev_b32_e32 v65, 16, v105
	v_lshlrev_b32_e32 v77, 16, v109
	v_and_b32_e32 v69, 0xffff0000, v105
	v_and_b32_e32 v81, 0xffff0000, v109
	v_add_f32_e32 v65, v65, v77
	v_add_f32_e32 v69, v69, v81
	v_mul_f32_e32 v73, v65, v65
	v_mul_f32_e32 v77, v69, v69
	v_add_f32_e32 v73, v73, v77
	v_lshlrev_b32_e32 v66, 16, v106
	v_lshlrev_b32_e32 v78, 16, v110
	v_and_b32_e32 v70, 0xffff0000, v106
	v_and_b32_e32 v82, 0xffff0000, v110
	v_add_f32_e32 v66, v66, v78
	v_add_f32_e32 v70, v70, v82
	v_mul_f32_e32 v74, v66, v66
	v_mul_f32_e32 v78, v70, v70
	v_add_f32_e32 v74, v74, v78
	v_lshlrev_b32_e32 v67, 16, v107
	v_lshlrev_b32_e32 v79, 16, v111
	v_and_b32_e32 v71, 0xffff0000, v107
	v_and_b32_e32 v83, 0xffff0000, v111
	v_add_f32_e32 v67, v67, v79
	v_add_f32_e32 v71, v71, v83
	v_mul_f32_e32 v75, v67, v67
	v_mul_f32_e32 v79, v71, v71
	v_add_f32_e32 v75, v75, v79
	ds_bpermute_b32 v76, v8, v72
	ds_bpermute_b32 v77, v8, v73
	ds_bpermute_b32 v78, v8, v74
	ds_bpermute_b32 v79, v8, v75
	s_waitcnt lgkmcnt(3)
	v_add_f32_e32 v72, v72, v76
	s_waitcnt lgkmcnt(2)
	v_add_f32_e32 v73, v73, v77
	s_waitcnt lgkmcnt(1)
	v_add_f32_e32 v74, v74, v78
	s_waitcnt lgkmcnt(0)
	v_add_f32_e32 v75, v75, v79
	ds_bpermute_b32 v76, v9, v72
	ds_bpermute_b32 v77, v9, v73
	ds_bpermute_b32 v78, v9, v74
	ds_bpermute_b32 v79, v9, v75
	s_waitcnt lgkmcnt(3)
	v_add_f32_e32 v72, v72, v76
	s_waitcnt lgkmcnt(2)
	v_add_f32_e32 v73, v73, v77
	s_waitcnt lgkmcnt(1)
	v_add_f32_e32 v74, v74, v78
	s_waitcnt lgkmcnt(0)
	v_add_f32_e32 v75, v75, v79
	ds_bpermute_b32 v76, v10, v72
	ds_bpermute_b32 v77, v10, v73
	ds_bpermute_b32 v78, v10, v74
	ds_bpermute_b32 v79, v10, v75
	s_waitcnt lgkmcnt(3)
	v_add_f32_e32 v72, v72, v76
	s_waitcnt lgkmcnt(2)
	v_add_f32_e32 v73, v73, v77
	s_waitcnt lgkmcnt(1)
	v_add_f32_e32 v74, v74, v78
	s_waitcnt lgkmcnt(0)
	v_add_f32_e32 v75, v75, v79
	ds_bpermute_b32 v76, v11, v72
	ds_bpermute_b32 v77, v11, v73
	ds_bpermute_b32 v78, v11, v74
	ds_bpermute_b32 v79, v11, v75
	s_waitcnt lgkmcnt(3)
	v_add_f32_e32 v72, v72, v76
	s_waitcnt lgkmcnt(2)
	v_add_f32_e32 v73, v73, v77
	s_waitcnt lgkmcnt(1)
	v_add_f32_e32 v74, v74, v78
	s_waitcnt lgkmcnt(0)
	v_add_f32_e32 v75, v75, v79
	ds_bpermute_b32 v76, v12, v72
	ds_bpermute_b32 v77, v12, v73
	ds_bpermute_b32 v78, v12, v74
	ds_bpermute_b32 v79, v12, v75
	s_waitcnt lgkmcnt(3)
	v_add_f32_e32 v72, v72, v76
	s_waitcnt lgkmcnt(2)
	v_add_f32_e32 v73, v73, v77
	s_waitcnt lgkmcnt(1)
	v_add_f32_e32 v74, v74, v78
	s_waitcnt lgkmcnt(0)
	v_add_f32_e32 v75, v75, v79
	ds_bpermute_b32 v76, v13, v72
	ds_bpermute_b32 v77, v13, v73
	ds_bpermute_b32 v78, v13, v74
	ds_bpermute_b32 v79, v13, v75
	s_waitcnt lgkmcnt(3)
	v_add_f32_e32 v72, v72, v76
	s_waitcnt lgkmcnt(2)
	v_add_f32_e32 v73, v73, v77
	s_waitcnt lgkmcnt(1)
	v_add_f32_e32 v74, v74, v78
	s_waitcnt lgkmcnt(0)
	v_add_f32_e32 v75, v75, v79
	v_fmamk_f32 v80, v72, 0x3c000000, v14
	v_mul_f32_e32 v76, 0x4b800000, v80
	v_cmp_gt_f32_e32 vcc, s14, v80
	s_nop 1
	v_cndmask_b32_e32 v80, v80, v76, vcc
	v_rsq_f32_e32 v80, v80
	s_nop 0
	v_mul_f32_e32 v76, 0x45800000, v80
	v_cndmask_b32_e32 v80, v80, v76, vcc
	v_mul_f32_e32 v64, v64, v80
	v_mul_f32_e32 v68, v68, v80
	v_mul_f32_e32 v64, v2, v64
	v_mul_f32_e32 v68, v3, v68
	v_lshlrev_b32_e32 v76, 16, v112
	v_and_b32_e32 v72, 0xffff0000, v112
	v_mul_f32_e32 v64, v64, v76
	v_mul_f32_e32 v68, v68, v72
	v_cvt_pk_bf16_f32 v64, v64, v68
	global_store_dword v[98:99], v64, off
	v_fmamk_f32 v81, v73, 0x3c000000, v14
	v_mul_f32_e32 v77, 0x4b800000, v81
	v_cmp_gt_f32_e32 vcc, s14, v81
	s_nop 1
	v_cndmask_b32_e32 v81, v81, v77, vcc
	v_rsq_f32_e32 v81, v81
	s_nop 0
	v_mul_f32_e32 v77, 0x45800000, v81
	v_cndmask_b32_e32 v81, v81, v77, vcc
	v_mul_f32_e32 v65, v65, v81
	v_mul_f32_e32 v69, v69, v81
	v_mul_f32_e32 v65, v2, v65
	v_mul_f32_e32 v69, v3, v69
	v_lshlrev_b32_e32 v77, 16, v113
	v_and_b32_e32 v73, 0xffff0000, v113
	v_mul_f32_e32 v65, v65, v77
	v_mul_f32_e32 v69, v69, v73
	v_cvt_pk_bf16_f32 v65, v65, v69
	global_store_dword v[98:99], v65, off offset:256
	v_fmamk_f32 v82, v74, 0x3c000000, v14
	v_mul_f32_e32 v78, 0x4b800000, v82
	v_cmp_gt_f32_e32 vcc, s14, v82
	s_nop 1
	v_cndmask_b32_e32 v82, v82, v78, vcc
	v_rsq_f32_e32 v82, v82
	s_nop 0
	v_mul_f32_e32 v78, 0x45800000, v82
	v_cndmask_b32_e32 v82, v82, v78, vcc
	v_mul_f32_e32 v66, v66, v82
	v_mul_f32_e32 v70, v70, v82
	v_mul_f32_e32 v66, v2, v66
	v_mul_f32_e32 v70, v3, v70
	v_lshlrev_b32_e32 v78, 16, v114
	v_and_b32_e32 v74, 0xffff0000, v114
	v_mul_f32_e32 v66, v66, v78
	v_mul_f32_e32 v70, v70, v74
	v_cvt_pk_bf16_f32 v66, v66, v70
	global_store_dword v[98:99], v66, off offset:512
	v_fmamk_f32 v83, v75, 0x3c000000, v14
	v_mul_f32_e32 v79, 0x4b800000, v83
	v_cmp_gt_f32_e32 vcc, s14, v83
	s_nop 1
	v_cndmask_b32_e32 v83, v83, v79, vcc
	v_rsq_f32_e32 v83, v83
	s_nop 0
	v_mul_f32_e32 v79, 0x45800000, v83
	v_cndmask_b32_e32 v83, v83, v79, vcc
	v_mul_f32_e32 v67, v67, v83
	v_mul_f32_e32 v71, v71, v83
	v_mul_f32_e32 v67, v2, v67
	v_mul_f32_e32 v71, v3, v71
	v_lshlrev_b32_e32 v79, 16, v115
	v_and_b32_e32 v75, 0xffff0000, v115
	v_mul_f32_e32 v67, v67, v79
	v_mul_f32_e32 v71, v71, v75
	v_cvt_pk_bf16_f32 v67, v67, v71
	global_store_dword v[98:99], v67, off offset:768
	v_lshl_add_u64 v[98:99], v[98:99], 0, s[16:17]
	s_waitcnt vmcnt(36)
; DI unsigned cvt_pk_bf16(float lo, float hi) { unsigned r; asm("v_cvt_pk_bf16_f32 %0, %1, %2" : "=v"(r) : "v"(lo), "v"(hi)); return r; }
; DI void phase_combine(const Params& p) {
;     ...
; #pragma unroll
;     for (int hh = 0; hh < 4; ++hh) {
;       const float o0 = __uint_as_float(a[hh] << 16) + __uint_as_float(b[hh] << 16), o1 = __uint_as_float(a[hh] & 0xffff0000u) + __uint_as_float(b[hh] & 0xffff0000u);
;       const float ss = wave_sum(o0 * o0 + o1 * o1);
;       const float rstd = rsqrtf(ss * (1.f / 128.f) + EPSN);
;       const float g0 = __uint_as_float(g[hh] << 16), g1 = __uint_as_float(g[hh] & 0xffff0000u);
;       *(unsigned*)(OC + (size_t)tok * 1024 + 512 + hh * 128 + lane * 2) = cvt_pk_bf16(o0 * rstd * w0 * g0, o1 * rstd * w1 * g1);
;     }
	v_lshlrev_b32_e32 v64, 16, v116
	v_lshlrev_b32_e32 v76, 16, v120
	v_and_b32_e32 v68, 0xffff0000, v116
	v_and_b32_e32 v80, 0xffff0000, v120
	v_add_f32_e32 v64, v64, v76
	v_add_f32_e32 v68, v68, v80
	v_mul_f32_e32 v72, v64, v64
	v_mul_f32_e32 v76, v68, v68
	v_add_f32_e32 v72, v72, v76
	v_lshlrev_b32_e32 v65, 16, v117
	v_lshlrev_b32_e32 v77, 16, v121
	v_and_b32_e32 v69, 0xffff0000, v117
	v_and_b32_e32 v81, 0xffff0000, v121
	v_add_f32_e32 v65, v65, v77
	v_add_f32_e32 v69, v69, v81
	v_mul_f32_e32 v73, v65, v65
	v_mul_f32_e32 v77, v69, v69
	v_add_f32_e32 v73, v73, v77
	v_lshlrev_b32_e32 v66, 16, v118
	v_lshlrev_b32_e32 v78, 16, v122
	v_and_b32_e32 v70, 0xffff0000, v118
	v_and_b32_e32 v82, 0xffff0000, v122
	v_add_f32_e32 v66, v66, v78
	v_add_f32_e32 v70, v70, v82
	v_mul_f32_e32 v74, v66, v66
	v_mul_f32_e32 v78, v70, v70
	v_add_f32_e32 v74, v74, v78
	v_lshlrev_b32_e32 v67, 16, v119
	v_lshlrev_b32_e32 v79, 16, v123
	v_and_b32_e32 v71, 0xffff0000, v119
	v_and_b32_e32 v83, 0xffff0000, v123
	v_add_f32_e32 v67, v67, v79
	v_add_f32_e32 v71, v71, v83
	v_mul_f32_e32 v75, v67, v67
	v_mul_f32_e32 v79, v71, v71
	v_add_f32_e32 v75, v75, v79
	ds_bpermute_b32 v76, v8, v72
	ds_bpermute_b32 v77, v8, v73
	ds_bpermute_b32 v78, v8, v74
	ds_bpermute_b32 v79, v8, v75
	s_waitcnt lgkmcnt(3)
	v_add_f32_e32 v72, v72, v76
	s_waitcnt lgkmcnt(2)
	v_add_f32_e32 v73, v73, v77
	s_waitcnt lgkmcnt(1)
	v_add_f32_e32 v74, v74, v78
	s_waitcnt lgkmcnt(0)
	v_add_f32_e32 v75, v75, v79
	ds_bpermute_b32 v76, v9, v72
	ds_bpermute_b32 v77, v9, v73
	ds_bpermute_b32 v78, v9, v74
	ds_bpermute_b32 v79, v9, v75
	s_waitcnt lgkmcnt(3)
	v_add_f32_e32 v72, v72, v76
	s_waitcnt lgkmcnt(2)
	v_add_f32_e32 v73, v73, v77
	s_waitcnt lgkmcnt(1)
	v_add_f32_e32 v74, v74, v78
	s_waitcnt lgkmcnt(0)
	v_add_f32_e32 v75, v75, v79
	ds_bpermute_b32 v76, v10, v72
	ds_bpermute_b32 v77, v10, v73
	ds_bpermute_b32 v78, v10, v74
	ds_bpermute_b32 v79, v10, v75
	s_waitcnt lgkmcnt(3)
	v_add_f32_e32 v72, v72, v76
	s_waitcnt lgkmcnt(2)
	v_add_f32_e32 v73, v73, v77
	s_waitcnt lgkmcnt(1)
	v_add_f32_e32 v74, v74, v78
	s_waitcnt lgkmcnt(0)
	v_add_f32_e32 v75, v75, v79
	ds_bpermute_b32 v76, v11, v72
	ds_bpermute_b32 v77, v11, v73
	ds_bpermute_b32 v78, v11, v74
	ds_bpermute_b32 v79, v11, v75
	s_waitcnt lgkmcnt(3)
	v_add_f32_e32 v72, v72, v76
	s_waitcnt lgkmcnt(2)
	v_add_f32_e32 v73, v73, v77
	s_waitcnt lgkmcnt(1)
	v_add_f32_e32 v74, v74, v78
	s_waitcnt lgkmcnt(0)
	v_add_f32_e32 v75, v75, v79
	ds_bpermute_b32 v76, v12, v72
	ds_bpermute_b32 v77, v12, v73
	ds_bpermute_b32 v78, v12, v74
	ds_bpermute_b32 v79, v12, v75
	s_waitcnt lgkmcnt(3)
	v_add_f32_e32 v72, v72, v76
	s_waitcnt lgkmcnt(2)
	v_add_f32_e32 v73, v73, v77
	s_waitcnt lgkmcnt(1)
	v_add_f32_e32 v74, v74, v78
	s_waitcnt lgkmcnt(0)
	v_add_f32_e32 v75, v75, v79
	ds_bpermute_b32 v76, v13, v72
	ds_bpermute_b32 v77, v13, v73
	ds_bpermute_b32 v78, v13, v74
	ds_bpermute_b32 v79, v13, v75
	s_waitcnt lgkmcnt(3)
	v_add_f32_e32 v72, v72, v76
	s_waitcnt lgkmcnt(2)
	v_add_f32_e32 v73, v73, v77
	s_waitcnt lgkmcnt(1)
	v_add_f32_e32 v74, v74, v78
	s_waitcnt lgkmcnt(0)
	v_add_f32_e32 v75, v75, v79
	v_fmamk_f32 v80, v72, 0x3c000000, v14
	v_mul_f32_e32 v76, 0x4b800000, v80
	v_cmp_gt_f32_e32 vcc, s14, v80
	s_nop 1
	v_cndmask_b32_e32 v80, v80, v76, vcc
	v_rsq_f32_e32 v80, v80
	s_nop 0
	v_mul_f32_e32 v76, 0x45800000, v80
	v_cndmask_b32_e32 v80, v80, v76, vcc
	v_mul_f32_e32 v64, v64, v80
	v_mul_f32_e32 v68, v68, v80
	v_mul_f32_e32 v64, v2, v64
	v_mul_f32_e32 v68, v3, v68
	v_lshlrev_b32_e32 v76, 16, v124
	v_and_b32_e32 v72, 0xffff0000, v124
	v_mul_f32_e32 v64, v64, v76
	v_mul_f32_e32 v68, v68, v72
	v_cvt_pk_bf16_f32 v64, v64, v68
	global_store_dword v[98:99], v64, off
	v_fmamk_f32 v81, v73, 0x3c000000, v14
	v_mul_f32_e32 v77, 0x4b800000, v81
	v_cmp_gt_f32_e32 vcc, s14, v81
	s_nop 1
	v_cndmask_b32_e32 v81, v81, v77, vcc
	v_rsq_f32_e32 v81, v81
	s_nop 0
	v_mul_f32_e32 v77, 0x45800000, v81
	v_cndmask_b32_e32 v81, v81, v77, vcc
	v_mul_f32_e32 v65, v65, v81
	v_mul_f32_e32 v69, v69, v81
	v_mul_f32_e32 v65, v2, v65
	v_mul_f32_e32 v69, v3, v69
	v_lshlrev_b32_e32 v77, 16, v125
	v_and_b32_e32 v73, 0xffff0000, v125
	v_mul_f32_e32 v65, v65, v77
	v_mul_f32_e32 v69, v69, v73
	v_cvt_pk_bf16_f32 v65, v65, v69
	global_store_dword v[98:99], v65, off offset:256
	v_fmamk_f32 v82, v74, 0x3c000000, v14
	v_mul_f32_e32 v78, 0x4b800000, v82
	v_cmp_gt_f32_e32 vcc, s14, v82
	s_nop 1
	v_cndmask_b32_e32 v82, v82, v78, vcc
	v_rsq_f32_e32 v82, v82
	s_nop 0
	v_mul_f32_e32 v78, 0x45800000, v82
	v_cndmask_b32_e32 v82, v82, v78, vcc
	v_mul_f32_e32 v66, v66, v82
	v_mul_f32_e32 v70, v70, v82
	v_mul_f32_e32 v66, v2, v66
	v_mul_f32_e32 v70, v3, v70
	v_lshlrev_b32_e32 v78, 16, v126
	v_and_b32_e32 v74, 0xffff0000, v126
	v_mul_f32_e32 v66, v66, v78
	v_mul_f32_e32 v70, v70, v74
	v_cvt_pk_bf16_f32 v66, v66, v70
	global_store_dword v[98:99], v66, off offset:512
	v_fmamk_f32 v83, v75, 0x3c000000, v14
	v_mul_f32_e32 v79, 0x4b800000, v83
	v_cmp_gt_f32_e32 vcc, s14, v83
	s_nop 1
	v_cndmask_b32_e32 v83, v83, v79, vcc
	v_rsq_f32_e32 v83, v83
	s_nop 0
	v_mul_f32_e32 v79, 0x45800000, v83
	v_cndmask_b32_e32 v83, v83, v79, vcc
	v_mul_f32_e32 v67, v67, v83
	v_mul_f32_e32 v71, v71, v83
	v_mul_f32_e32 v67, v2, v67
	v_mul_f32_e32 v71, v3, v71
	v_lshlrev_b32_e32 v79, 16, v127
	v_and_b32_e32 v75, 0xffff0000, v127
	v_mul_f32_e32 v67, v67, v79
	v_mul_f32_e32 v71, v71, v75
	v_cvt_pk_bf16_f32 v67, v67, v71
	global_store_dword v[98:99], v67, off offset:768
	v_lshl_add_u64 v[98:99], v[98:99], 0, s[16:17]
	s_waitcnt vmcnt(24)
; DI unsigned cvt_pk_bf16(float lo, float hi) { unsigned r; asm("v_cvt_pk_bf16_f32 %0, %1, %2" : "=v"(r) : "v"(lo), "v"(hi)); return r; }
; DI void phase_combine(const Params& p) {
;     ...
; #pragma unroll
;     for (int hh = 0; hh < 4; ++hh) {
;       const float o0 = __uint_as_float(a[hh] << 16) + __uint_as_float(b[hh] << 16), o1 = __uint_as_float(a[hh] & 0xffff0000u) + __uint_as_float(b[hh] & 0xffff0000u);
;       const float ss = wave_sum(o0 * o0 + o1 * o1);
;       const float rstd = rsqrtf(ss * (1.f / 128.f) + EPSN);
;       const float g0 = __uint_as_float(g[hh] << 16), g1 = __uint_as_float(g[hh] & 0xffff0000u);
;       *(unsigned*)(OC + (size_t)tok * 1024 + 512 + hh * 128 + lane * 2) = cvt_pk_bf16(o0 * rstd * w0 * g0, o1 * rstd * w1 * g1);
;     }
	v_lshlrev_b32_e32 v64, 16, v128
	v_lshlrev_b32_e32 v76, 16, v132
	v_and_b32_e32 v68, 0xffff0000, v128
	v_and_b32_e32 v80, 0xffff0000, v132
	v_add_f32_e32 v64, v64, v76
	v_add_f32_e32 v68, v68, v80
	v_mul_f32_e32 v72, v64, v64
	v_mul_f32_e32 v76, v68, v68
	v_add_f32_e32 v72, v72, v76
	v_lshlrev_b32_e32 v65, 16, v129
	v_lshlrev_b32_e32 v77, 16, v133
	v_and_b32_e32 v69, 0xffff0000, v129
	v_and_b32_e32 v81, 0xffff0000, v133
	v_add_f32_e32 v65, v65, v77
	v_add_f32_e32 v69, v69, v81
	v_mul_f32_e32 v73, v65, v65
	v_mul_f32_e32 v77, v69, v69
	v_add_f32_e32 v73, v73, v77
	v_lshlrev_b32_e32 v66, 16, v130
	v_lshlrev_b32_e32 v78, 16, v134
	v_and_b32_e32 v70, 0xffff0000, v130
	v_and_b32_e32 v82, 0xffff0000, v134
	v_add_f32_e32 v66, v66, v78
	v_add_f32_e32 v70, v70, v82
	v_mul_f32_e32 v74, v66, v66
	v_mul_f32_e32 v78, v70, v70
	v_add_f32_e32 v74, v74, v78
	v_lshlrev_b32_e32 v67, 16, v131
	v_lshlrev_b32_e32 v79, 16, v135
	v_and_b32_e32 v71, 0xffff0000, v131
	v_and_b32_e32 v83, 0xffff0000, v135
	v_add_f32_e32 v67, v67, v79
	v_add_f32_e32 v71, v71, v83
	v_mul_f32_e32 v75, v67, v67
	v_mul_f32_e32 v79, v71, v71
	v_add_f32_e32 v75, v75, v79
	ds_bpermute_b32 v76, v8, v72
	ds_bpermute_b32 v77, v8, v73
	ds_bpermute_b32 v78, v8, v74
	ds_bpermute_b32 v79, v8, v75
	s_waitcnt lgkmcnt(3)
	v_add_f32_e32 v72, v72, v76
	s_waitcnt lgkmcnt(2)
	v_add_f32_e32 v73, v73, v77
	s_waitcnt lgkmcnt(1)
	v_add_f32_e32 v74, v74, v78
	s_waitcnt lgkmcnt(0)
	v_add_f32_e32 v75, v75, v79
	ds_bpermute_b32 v76, v9, v72
	ds_bpermute_b32 v77, v9, v73
	ds_bpermute_b32 v78, v9, v74
	ds_bpermute_b32 v79, v9, v75
	s_waitcnt lgkmcnt(3)
	v_add_f32_e32 v72, v72, v76
	s_waitcnt lgkmcnt(2)
	v_add_f32_e32 v73, v73, v77
	s_waitcnt lgkmcnt(1)
	v_add_f32_e32 v74, v74, v78
	s_waitcnt lgkmcnt(0)
	v_add_f32_e32 v75, v75, v79
	ds_bpermute_b32 v76, v10, v72
	ds_bpermute_b32 v77, v10, v73
	ds_bpermute_b32 v78, v10, v74
	ds_bpermute_b32 v79, v10, v75
	s_waitcnt lgkmcnt(3)
	v_add_f32_e32 v72, v72, v76
	s_waitcnt lgkmcnt(2)
	v_add_f32_e32 v73, v73, v77
	s_waitcnt lgkmcnt(1)
	v_add_f32_e32 v74, v74, v78
	s_waitcnt lgkmcnt(0)
	v_add_f32_e32 v75, v75, v79
	ds_bpermute_b32 v76, v11, v72
	ds_bpermute_b32 v77, v11, v73
	ds_bpermute_b32 v78, v11, v74
	ds_bpermute_b32 v79, v11, v75
	s_waitcnt lgkmcnt(3)
	v_add_f32_e32 v72, v72, v76
	s_waitcnt lgkmcnt(2)
	v_add_f32_e32 v73, v73, v77
	s_waitcnt lgkmcnt(1)
	v_add_f32_e32 v74, v74, v78
	s_waitcnt lgkmcnt(0)
	v_add_f32_e32 v75, v75, v79
	ds_bpermute_b32 v76, v12, v72
	ds_bpermute_b32 v77, v12, v73
	ds_bpermute_b32 v78, v12, v74
	ds_bpermute_b32 v79, v12, v75
	s_waitcnt lgkmcnt(3)
	v_add_f32_e32 v72, v72, v76
	s_waitcnt lgkmcnt(2)
	v_add_f32_e32 v73, v73, v77
	s_waitcnt lgkmcnt(1)
	v_add_f32_e32 v74, v74, v78
	s_waitcnt lgkmcnt(0)
	v_add_f32_e32 v75, v75, v79
	ds_bpermute_b32 v76, v13, v72
	ds_bpermute_b32 v77, v13, v73
	ds_bpermute_b32 v78, v13, v74
	ds_bpermute_b32 v79, v13, v75
	s_waitcnt lgkmcnt(3)
	v_add_f32_e32 v72, v72, v76
	s_waitcnt lgkmcnt(2)
	v_add_f32_e32 v73, v73, v77
	s_waitcnt lgkmcnt(1)
	v_add_f32_e32 v74, v74, v78
	s_waitcnt lgkmcnt(0)
	v_add_f32_e32 v75, v75, v79
	v_fmamk_f32 v80, v72, 0x3c000000, v14
	v_mul_f32_e32 v76, 0x4b800000, v80
	v_cmp_gt_f32_e32 vcc, s14, v80
	s_nop 1
	v_cndmask_b32_e32 v80, v80, v76, vcc
	v_rsq_f32_e32 v80, v80
	s_nop 0
	v_mul_f32_e32 v76, 0x45800000, v80
	v_cndmask_b32_e32 v80, v80, v76, vcc
	v_mul_f32_e32 v64, v64, v80
	v_mul_f32_e32 v68, v68, v80
	v_mul_f32_e32 v64, v2, v64
	v_mul_f32_e32 v68, v3, v68
	v_lshlrev_b32_e32 v76, 16, v136
	v_and_b32_e32 v72, 0xffff0000, v136
	v_mul_f32_e32 v64, v64, v76
	v_mul_f32_e32 v68, v68, v72
	v_cvt_pk_bf16_f32 v64, v64, v68
	global_store_dword v[98:99], v64, off
	v_fmamk_f32 v81, v73, 0x3c000000, v14
	v_mul_f32_e32 v77, 0x4b800000, v81
	v_cmp_gt_f32_e32 vcc, s14, v81
	s_nop 1
	v_cndmask_b32_e32 v81, v81, v77, vcc
	v_rsq_f32_e32 v81, v81
	s_nop 0
	v_mul_f32_e32 v77, 0x45800000, v81
	v_cndmask_b32_e32 v81, v81, v77, vcc
	v_mul_f32_e32 v65, v65, v81
	v_mul_f32_e32 v69, v69, v81
	v_mul_f32_e32 v65, v2, v65
	v_mul_f32_e32 v69, v3, v69
	v_lshlrev_b32_e32 v77, 16, v137
	v_and_b32_e32 v73, 0xffff0000, v137
	v_mul_f32_e32 v65, v65, v77
	v_mul_f32_e32 v69, v69, v73
	v_cvt_pk_bf16_f32 v65, v65, v69
	global_store_dword v[98:99], v65, off offset:256
	v_fmamk_f32 v82, v74, 0x3c000000, v14
	v_mul_f32_e32 v78, 0x4b800000, v82
	v_cmp_gt_f32_e32 vcc, s14, v82
	s_nop 1
	v_cndmask_b32_e32 v82, v82, v78, vcc
	v_rsq_f32_e32 v82, v82
	s_nop 0
	v_mul_f32_e32 v78, 0x45800000, v82
	v_cndmask_b32_e32 v82, v82, v78, vcc
	v_mul_f32_e32 v66, v66, v82
	v_mul_f32_e32 v70, v70, v82
	v_mul_f32_e32 v66, v2, v66
	v_mul_f32_e32 v70, v3, v70
	v_lshlrev_b32_e32 v78, 16, v138
	v_and_b32_e32 v74, 0xffff0000, v138
	v_mul_f32_e32 v66, v66, v78
	v_mul_f32_e32 v70, v70, v74
	v_cvt_pk_bf16_f32 v66, v66, v70
	global_store_dword v[98:99], v66, off offset:512
	v_fmamk_f32 v83, v75, 0x3c000000, v14
	v_mul_f32_e32 v79, 0x4b800000, v83
	v_cmp_gt_f32_e32 vcc, s14, v83
	s_nop 1
	v_cndmask_b32_e32 v83, v83, v79, vcc
	v_rsq_f32_e32 v83, v83
	s_nop 0
	v_mul_f32_e32 v79, 0x45800000, v83
	v_cndmask_b32_e32 v83, v83, v79, vcc
	v_mul_f32_e32 v67, v67, v83
	v_mul_f32_e32 v71, v71, v83
	v_mul_f32_e32 v67, v2, v67
	v_mul_f32_e32 v71, v3, v71
	v_lshlrev_b32_e32 v79, 16, v139
	v_and_b32_e32 v75, 0xffff0000, v139
	v_mul_f32_e32 v67, v67, v79
	v_mul_f32_e32 v71, v71, v75
	v_cvt_pk_bf16_f32 v67, v67, v71
	global_store_dword v[98:99], v67, off offset:768
	v_lshl_add_u64 v[98:99], v[98:99], 0, s[16:17]
	s_waitcnt vmcnt(12)
; DI unsigned cvt_pk_bf16(float lo, float hi) { unsigned r; asm("v_cvt_pk_bf16_f32 %0, %1, %2" : "=v"(r) : "v"(lo), "v"(hi)); return r; }
; DI void phase_combine(const Params& p) {
;     ...
; #pragma unroll
;     for (int hh = 0; hh < 4; ++hh) {
;       const float o0 = __uint_as_float(a[hh] << 16) + __uint_as_float(b[hh] << 16), o1 = __uint_as_float(a[hh] & 0xffff0000u) + __uint_as_float(b[hh] & 0xffff0000u);
;       const float ss = wave_sum(o0 * o0 + o1 * o1);
;       const float rstd = rsqrtf(ss * (1.f / 128.f) + EPSN);
;       const float g0 = __uint_as_float(g[hh] << 16), g1 = __uint_as_float(g[hh] & 0xffff0000u);
;       *(unsigned*)(OC + (size_t)tok * 1024 + 512 + hh * 128 + lane * 2) = cvt_pk_bf16(o0 * rstd * w0 * g0, o1 * rstd * w1 * g1);
;     }
	v_lshlrev_b32_e32 v64, 16, v140
	v_lshlrev_b32_e32 v76, 16, v144
	v_and_b32_e32 v68, 0xffff0000, v140
	v_and_b32_e32 v80, 0xffff0000, v144
	v_add_f32_e32 v64, v64, v76
	v_add_f32_e32 v68, v68, v80
	v_mul_f32_e32 v72, v64, v64
	v_mul_f32_e32 v76, v68, v68
	v_add_f32_e32 v72, v72, v76
	v_lshlrev_b32_e32 v65, 16, v141
	v_lshlrev_b32_e32 v77, 16, v145
	v_and_b32_e32 v69, 0xffff0000, v141
	v_and_b32_e32 v81, 0xffff0000, v145
	v_add_f32_e32 v65, v65, v77
	v_add_f32_e32 v69, v69, v81
	v_mul_f32_e32 v73, v65, v65
	v_mul_f32_e32 v77, v69, v69
	v_add_f32_e32 v73, v73, v77
	v_lshlrev_b32_e32 v66, 16, v142
	v_lshlrev_b32_e32 v78, 16, v146
	v_and_b32_e32 v70, 0xffff0000, v142
	v_and_b32_e32 v82, 0xffff0000, v146
	v_add_f32_e32 v66, v66, v78
	v_add_f32_e32 v70, v70, v82
	v_mul_f32_e32 v74, v66, v66
	v_mul_f32_e32 v78, v70, v70
	v_add_f32_e32 v74, v74, v78
	v_lshlrev_b32_e32 v67, 16, v143
	v_lshlrev_b32_e32 v79, 16, v147
	v_and_b32_e32 v71, 0xffff0000, v143
	v_and_b32_e32 v83, 0xffff0000, v147
	v_add_f32_e32 v67, v67, v79
	v_add_f32_e32 v71, v71, v83
	v_mul_f32_e32 v75, v67, v67
	v_mul_f32_e32 v79, v71, v71
	v_add_f32_e32 v75, v75, v79
	ds_bpermute_b32 v76, v8, v72
	ds_bpermute_b32 v77, v8, v73
	ds_bpermute_b32 v78, v8, v74
	ds_bpermute_b32 v79, v8, v75
	s_waitcnt lgkmcnt(3)
	v_add_f32_e32 v72, v72, v76
	s_waitcnt lgkmcnt(2)
	v_add_f32_e32 v73, v73, v77
	s_waitcnt lgkmcnt(1)
	v_add_f32_e32 v74, v74, v78
	s_waitcnt lgkmcnt(0)
	v_add_f32_e32 v75, v75, v79
	ds_bpermute_b32 v76, v9, v72
	ds_bpermute_b32 v77, v9, v73
	ds_bpermute_b32 v78, v9, v74
	ds_bpermute_b32 v79, v9, v75
	s_waitcnt lgkmcnt(3)
	v_add_f32_e32 v72, v72, v76
	s_waitcnt lgkmcnt(2)
	v_add_f32_e32 v73, v73, v77
	s_waitcnt lgkmcnt(1)
	v_add_f32_e32 v74, v74, v78
	s_waitcnt lgkmcnt(0)
	v_add_f32_e32 v75, v75, v79
	ds_bpermute_b32 v76, v10, v72
	ds_bpermute_b32 v77, v10, v73
	ds_bpermute_b32 v78, v10, v74
	ds_bpermute_b32 v79, v10, v75
	s_waitcnt lgkmcnt(3)
	v_add_f32_e32 v72, v72, v76
	s_waitcnt lgkmcnt(2)
	v_add_f32_e32 v73, v73, v77
	s_waitcnt lgkmcnt(1)
	v_add_f32_e32 v74, v74, v78
	s_waitcnt lgkmcnt(0)
	v_add_f32_e32 v75, v75, v79
	ds_bpermute_b32 v76, v11, v72
	ds_bpermute_b32 v77, v11, v73
	ds_bpermute_b32 v78, v11, v74
	ds_bpermute_b32 v79, v11, v75
	s_waitcnt lgkmcnt(3)
	v_add_f32_e32 v72, v72, v76
	s_waitcnt lgkmcnt(2)
	v_add_f32_e32 v73, v73, v77
	s_waitcnt lgkmcnt(1)
	v_add_f32_e32 v74, v74, v78
	s_waitcnt lgkmcnt(0)
	v_add_f32_e32 v75, v75, v79
	ds_bpermute_b32 v76, v12, v72
	ds_bpermute_b32 v77, v12, v73
	ds_bpermute_b32 v78, v12, v74
	ds_bpermute_b32 v79, v12, v75
	s_waitcnt lgkmcnt(3)
	v_add_f32_e32 v72, v72, v76
	s_waitcnt lgkmcnt(2)
	v_add_f32_e32 v73, v73, v77
	s_waitcnt lgkmcnt(1)
	v_add_f32_e32 v74, v74, v78
	s_waitcnt lgkmcnt(0)
	v_add_f32_e32 v75, v75, v79
	ds_bpermute_b32 v76, v13, v72
	ds_bpermute_b32 v77, v13, v73
	ds_bpermute_b32 v78, v13, v74
	ds_bpermute_b32 v79, v13, v75
	s_waitcnt lgkmcnt(3)
	v_add_f32_e32 v72, v72, v76
	s_waitcnt lgkmcnt(2)
	v_add_f32_e32 v73, v73, v77
	s_waitcnt lgkmcnt(1)
	v_add_f32_e32 v74, v74, v78
	s_waitcnt lgkmcnt(0)
	v_add_f32_e32 v75, v75, v79
	v_fmamk_f32 v80, v72, 0x3c000000, v14
	v_mul_f32_e32 v76, 0x4b800000, v80
	v_cmp_gt_f32_e32 vcc, s14, v80
	s_nop 1
	v_cndmask_b32_e32 v80, v80, v76, vcc
	v_rsq_f32_e32 v80, v80
	s_nop 0
	v_mul_f32_e32 v76, 0x45800000, v80
	v_cndmask_b32_e32 v80, v80, v76, vcc
	v_mul_f32_e32 v64, v64, v80
	v_mul_f32_e32 v68, v68, v80
	v_mul_f32_e32 v64, v2, v64
	v_mul_f32_e32 v68, v3, v68
	v_lshlrev_b32_e32 v76, 16, v148
	v_and_b32_e32 v72, 0xffff0000, v148
	v_mul_f32_e32 v64, v64, v76
	v_mul_f32_e32 v68, v68, v72
	v_cvt_pk_bf16_f32 v64, v64, v68
	global_store_dword v[98:99], v64, off
	v_fmamk_f32 v81, v73, 0x3c000000, v14
	v_mul_f32_e32 v77, 0x4b800000, v81
	v_cmp_gt_f32_e32 vcc, s14, v81
	s_nop 1
	v_cndmask_b32_e32 v81, v81, v77, vcc
	v_rsq_f32_e32 v81, v81
	s_nop 0
	v_mul_f32_e32 v77, 0x45800000, v81
	v_cndmask_b32_e32 v81, v81, v77, vcc
	v_mul_f32_e32 v65, v65, v81
	v_mul_f32_e32 v69, v69, v81
	v_mul_f32_e32 v65, v2, v65
	v_mul_f32_e32 v69, v3, v69
	v_lshlrev_b32_e32 v77, 16, v149
	v_and_b32_e32 v73, 0xffff0000, v149
	v_mul_f32_e32 v65, v65, v77
	v_mul_f32_e32 v69, v69, v73
	v_cvt_pk_bf16_f32 v65, v65, v69
	global_store_dword v[98:99], v65, off offset:256
	v_fmamk_f32 v82, v74, 0x3c000000, v14
	v_mul_f32_e32 v78, 0x4b800000, v82
	v_cmp_gt_f32_e32 vcc, s14, v82
	s_nop 1
	v_cndmask_b32_e32 v82, v82, v78, vcc
	v_rsq_f32_e32 v82, v82
	s_nop 0
	v_mul_f32_e32 v78, 0x45800000, v82
	v_cndmask_b32_e32 v82, v82, v78, vcc
	v_mul_f32_e32 v66, v66, v82
	v_mul_f32_e32 v70, v70, v82
	v_mul_f32_e32 v66, v2, v66
	v_mul_f32_e32 v70, v3, v70
	v_lshlrev_b32_e32 v78, 16, v150
	v_and_b32_e32 v74, 0xffff0000, v150
	v_mul_f32_e32 v66, v66, v78
	v_mul_f32_e32 v70, v70, v74
	v_cvt_pk_bf16_f32 v66, v66, v70
	global_store_dword v[98:99], v66, off offset:512
	v_fmamk_f32 v83, v75, 0x3c000000, v14
	v_mul_f32_e32 v79, 0x4b800000, v83
	v_cmp_gt_f32_e32 vcc, s14, v83
	s_nop 1
	v_cndmask_b32_e32 v83, v83, v79, vcc
	v_rsq_f32_e32 v83, v83
	s_nop 0
	v_mul_f32_e32 v79, 0x45800000, v83
	v_cndmask_b32_e32 v83, v83, v79, vcc
	v_mul_f32_e32 v67, v67, v83
	v_mul_f32_e32 v71, v71, v83
	v_mul_f32_e32 v67, v2, v67
	v_mul_f32_e32 v71, v3, v71
	v_lshlrev_b32_e32 v79, 16, v151
	v_and_b32_e32 v75, 0xffff0000, v151
	v_mul_f32_e32 v67, v67, v79
	v_mul_f32_e32 v71, v71, v75
	v_cvt_pk_bf16_f32 v67, v67, v71
	global_store_dword v[98:99], v67, off offset:768
	v_lshl_add_u64 v[98:99], v[98:99], 0, s[16:17]
	s_branch .LBB0_952
; DI unsigned cvt_pk_bf16(float lo, float hi) { unsigned r; asm("v_cvt_pk_bf16_f32 %0, %1, %2" : "=v"(r) : "v"(lo), "v"(hi)); return r; }
; DI void phase_combine(const Params& p) {
;   const int lane = threadIdx.x & 63, wave = threadIdx.x >> 6;
;   const unsigned* ofw = (const unsigned*)p.out; const unsigned* obw = (const unsigned*)((const bf16_t*)p.out + (size_t)NTOK * 512);
;   const unsigned* GH = (const unsigned*)(p.ws + WS_GH);
;   bf16_t* OC = (bf16_t*)(p.ws + WS_OCAT);
;   const float w0 = p.hgrn_norm_w[lane * 2], w1 = p.hgrn_norm_w[lane * 2 + 1];
;   for (int tok = blockIdx.x * 8 + wave; tok < NTOK; tok += gridDim.x * 8) {
;     unsigned a[4], b[4], g[4];
; #pragma unroll
;     for (int hh = 0; hh < 4; ++hh) { const size_t idx = ((size_t)tok * 512 + hh * 128 + lane * 2) >> 1; a[hh] = ofw[idx]; b[hh] = obw[idx]; g[hh] = GH[idx]; }
; #pragma unroll
;     for (int hh = 0; hh < 4; ++hh) {
;       const float o0 = __uint_as_float(a[hh] << 16) + __uint_as_float(b[hh] << 16), o1 = __uint_as_float(a[hh] & 0xffff0000u) + __uint_as_float(b[hh] & 0xffff0000u);
;       const float ss = wave_sum(o0 * o0 + o1 * o1);
;       const float rstd = rsqrtf(ss * (1.f / 128.f) + EPSN);
;       const float g0 = __uint_as_float(g[hh] << 16), g1 = __uint_as_float(g[hh] & 0xffff0000u);
;       *(unsigned*)(OC + (size_t)tok * 1024 + 512 + hh * 128 + lane * 2) = cvt_pk_bf16(o0 * rstd * w0 * g0, o1 * rstd * w1 * g1);
;     }
;   }
; }
	s_nop 0
	s_nop 0
	s_nop 0
	s_nop 0
	s_nop 0
	s_nop 0
	s_nop 0
	s_nop 0
	s_nop 0
	s_nop 0
	s_nop 0
	s_nop 0
	s_nop 0
	s_nop 0
	s_nop 0
	s_nop 0
	s_nop 0
	s_nop 0
	s_nop 0
	s_nop 0
	s_nop 0
	s_nop 0
	s_nop 0
	s_nop 0
	s_nop 0
	s_nop 0
	s_nop 0
	s_nop 0
	s_nop 0
	s_nop 0
	s_nop 0
	s_nop 0
	s_nop 0
	s_nop 0
	s_nop 0
	s_nop 0
	s_nop 0
	s_nop 0
	s_nop 0
	s_nop 0
	s_nop 0
	s_nop 0
	s_nop 0
	s_nop 0
	s_nop 0
	s_nop 0
	s_nop 0
	s_nop 0
	s_nop 0
	s_nop 0
	s_nop 0
	s_nop 0
	s_nop 0
	s_nop 0
	s_nop 0
	s_nop 0
	s_nop 0
	s_nop 0
	s_nop 0
	s_nop 0
	s_nop 0
	s_nop 0
	s_nop 0
	s_nop 0
	s_nop 0
	s_nop 0
	s_nop 0
	s_nop 0
	s_nop 0
	s_nop 0
	s_nop 0
	s_nop 0
	s_nop 0
	s_nop 0
	s_nop 0
	s_nop 0
	s_nop 0
	s_nop 0
	s_nop 0
	s_nop 0
	s_nop 0
	s_nop 0
	s_nop 0
	s_nop 0
	s_nop 0
	s_nop 0
	s_nop 0
	s_nop 0
	s_nop 0
	s_nop 0
	s_nop 0
	s_nop 0
	s_nop 0
	s_nop 0
	s_nop 0
	s_nop 0
	s_nop 0
	s_nop 0
	s_nop 0
	s_nop 0
	s_nop 0
	s_nop 0
	s_nop 0
	s_nop 0
	s_nop 0
	s_nop 0
	s_nop 0
	s_nop 0
	s_nop 0
	s_nop 0
	s_nop 0
	s_nop 0
	s_nop 0
	s_nop 0
	s_nop 0
	s_nop 0
	s_nop 0
	s_nop 0
	s_nop 0
	s_nop 0
	s_nop 0
	s_nop 0
	s_nop 0
	s_nop 0
	s_nop 0
	s_nop 0
	s_nop 0
	s_nop 0
	s_nop 0
	s_nop 0
	s_nop 0
	s_nop 0
	s_nop 0
	s_nop 0
	s_nop 0
	s_nop 0
	s_nop 0
	s_nop 0
	s_nop 0
	s_nop 0
	s_nop 0
	s_nop 0
	s_nop 0
	s_nop 0
	s_nop 0
	s_nop 0
	s_nop 0
	s_nop 0
	s_nop 0
	s_nop 0
	s_nop 0
	s_nop 0
	s_nop 0
	s_nop 0
	s_nop 0
	s_nop 0
	s_nop 0
	s_nop 0
	s_nop 0
	s_nop 0
	s_nop 0
	s_nop 0
	s_nop 0
	s_nop 0
	s_nop 0
	s_nop 0
	s_nop 0
	s_nop 0
	s_nop 0
	s_nop 0
	s_nop 0
	s_nop 0
	s_nop 0
	s_nop 0
	s_nop 0
	s_nop 0
	s_nop 0
	s_nop 0
	s_nop 0
	s_nop 0
	s_nop 0
	s_nop 0
	s_nop 0
	s_nop 0
	s_nop 0
	s_nop 0
	s_nop 0
	s_nop 0
	s_nop 0
	s_nop 0
	s_nop 0
	s_nop 0
	s_nop 0
	s_nop 0
	s_nop 0
	s_nop 0
	s_nop 0
	s_nop 0
	s_nop 0
	s_nop 0
	s_nop 0
	s_nop 0
	s_nop 0
	s_nop 0
	s_nop 0
	s_nop 0
	s_nop 0
	s_nop 0
	s_nop 0
	s_nop 0
	s_nop 0
	s_nop 0
	s_nop 0
	s_nop 0
	s_nop 0
	s_nop 0
	s_nop 0
	s_nop 0
	s_nop 0
	s_nop 0
	s_nop 0
	s_nop 0
	s_nop 0
	s_nop 0
	s_nop 0
	s_nop 0
	s_nop 0
	s_nop 0
	s_nop 0
	s_nop 0
	s_nop 0
	s_nop 0
	s_nop 0
	s_nop 0
	s_nop 0
	s_nop 0
	s_nop 0
	s_nop 0
	s_nop 0
	s_nop 0
	s_nop 0
	s_nop 0
	s_nop 0
	s_nop 0
	s_nop 0
	s_nop 0
	s_nop 0
	s_nop 0
	s_nop 0
	s_nop 0
	s_nop 0
	s_nop 0
	s_nop 0
	s_nop 0
	s_nop 0
	s_nop 0
